# GEMM epilogue row-sum-of-squares: ds_bpermute lane^16/lane^32 butterflies (32 serialized LDS round trips per tile) replaced by v_permlane16/32_swap; plus previous P8 epilogue edits
# baseline (speedup 1.0000x reference)
; #define LAS __attribute__((address_space(3)))
; #define EPI_BAR() do { asm volatile("s_waitcnt lgkmcnt(0)" ::: "memory"); __builtin_amdgcn_s_barrier(); asm volatile("" ::: "memory"); } while (0)
; __device__ __forceinline__ void head_ss(const f32x4 (&v)[2][2][4][2], float (&tot)[2][4][2], LAS float* X, int wr, int wc, int fr, int fq) {
; #pragma unroll
;     for (int ai = 0; ai < 2; ++ai)
; #pragma unroll
;         for (int m = 0; m < 4; ++m)
; #pragma unroll
;             for (int bj = 0; bj < 2; ++bj) {
;                 const f32x4 a = v[ai][bj][m][0], b = v[ai][bj][m][1];
;                 float s = (a[0] * a[0] + a[1] * a[1]) + (a[2] * a[2] + a[3] * a[3]) + (b[0] * b[0] + b[1] * b[1]) + (b[2] * b[2] + b[3] * b[3]);
;                 s += __shfl_xor(s, 16); s += __shfl_xor(s, 32);
;                 if (fq == 0) X[((ai * 128 + wr * 64 + m * 16 + fr) * 2 + bj) * 4 + wc] = s;
;             }
;     EPI_BAR();
.LBB0_233:
	s_and_b64 vcc, exec, s[0:1]
	s_cbranch_vccnz .LBB0_267
	v_mul_f32_e32 v94, v141, v141
	v_mul_f32_e32 v95, v143, v143
	v_fmac_f32_e32 v94, v140, v140
	v_fmac_f32_e32 v95, v142, v142
	v_and_b32_e32 v93, 64, v206
	v_add_f32_e32 v94, v94, v95
	v_mul_f32_e32 v95, v137, v137
	v_xor_b32_e32 v92, 16, v206
	v_add_u32_e32 v93, 64, v93
	v_fmac_f32_e32 v95, v136, v136
	v_cmp_lt_i32_e32 vcc, v92, v93
	v_add_f32_e32 v94, v94, v95
	v_mul_f32_e32 v95, v139, v139
	v_cndmask_b32_e32 v92, v206, v92, vcc
	v_fmac_f32_e32 v95, v138, v138
	v_lshlrev_b32_e32 v92, 2, v92
	v_add_f32_e32 v95, v95, v94
	v_mov_b32_e32 v100, v95
	s_nop 1
	v_permlane16_swap_b32_e32 v100, v95
	v_xor_b32_e32 v94, 32, v206
	v_cmp_lt_i32_e32 vcc, v94, v93
	v_readlane_b32 s7, v242, 47
	s_waitcnt lgkmcnt(0)
	v_add_f32_e32 v95, v95, v100
	v_cndmask_b32_e32 v93, v206, v94, vcc
	v_lshlrev_b32_e32 v94, 2, v93
	v_mov_b32_e32 v100, v95
	s_nop 1
	v_permlane32_swap_b32_e32 v100, v95
	v_add_u32_e32 v93, s7, v200
	s_and_saveexec_b64 s[20:21], s[8:9]
	s_cbranch_execz .LBB0_236
	s_waitcnt lgkmcnt(0)
	v_add_f32_e32 v95, v95, v100
	ds_write_b32 v93, v95
.LBB0_236:
	s_or_b64 exec, exec, s[20:21]
	v_mul_f32_e32 v95, v133, v133
	s_waitcnt lgkmcnt(0)
	v_mul_f32_e32 v100, v135, v135
	v_fmac_f32_e32 v95, v132, v132
	v_fmac_f32_e32 v100, v134, v134
	v_add_f32_e32 v95, v95, v100
	v_mul_f32_e32 v100, v129, v129
	v_fmac_f32_e32 v100, v128, v128
	v_add_f32_e32 v95, v95, v100
	v_mul_f32_e32 v100, v131, v131
	v_fmac_f32_e32 v100, v130, v130
	v_add_f32_e32 v95, v100, v95
	v_mov_b32_e32 v100, v95
	s_nop 1
	v_permlane16_swap_b32_e32 v100, v95
	s_waitcnt lgkmcnt(0)
	v_add_f32_e32 v95, v95, v100
	v_mov_b32_e32 v100, v95
	s_nop 1
	v_permlane32_swap_b32_e32 v100, v95
	s_and_saveexec_b64 s[20:21], s[8:9]
	s_cbranch_execz .LBB0_238
	s_waitcnt lgkmcnt(0)
	v_add_f32_e32 v95, v95, v100
	ds_write_b32 v93, v95 offset:16
.LBB0_238:
	s_or_b64 exec, exec, s[20:21]
	v_mul_f32_e32 v95, v125, v125
	s_waitcnt lgkmcnt(0)
	v_mul_f32_e32 v100, v127, v127
	v_fmac_f32_e32 v95, v124, v124
	v_fmac_f32_e32 v100, v126, v126
	v_add_f32_e32 v95, v95, v100
	v_mul_f32_e32 v100, v121, v121
	v_fmac_f32_e32 v100, v120, v120
	v_add_f32_e32 v95, v95, v100
	v_mul_f32_e32 v100, v123, v123
	v_fmac_f32_e32 v100, v122, v122
	v_add_f32_e32 v95, v100, v95
	v_mov_b32_e32 v100, v95
	s_nop 1
	v_permlane16_swap_b32_e32 v100, v95
	s_waitcnt lgkmcnt(0)
	v_add_f32_e32 v95, v95, v100
	v_mov_b32_e32 v100, v95
	s_nop 1
	v_permlane32_swap_b32_e32 v100, v95
	s_and_saveexec_b64 s[20:21], s[8:9]
	s_cbranch_execz .LBB0_240
	s_waitcnt lgkmcnt(0)
	v_add_f32_e32 v95, v95, v100
	ds_write_b32 v93, v95 offset:512
.LBB0_240:
	s_or_b64 exec, exec, s[20:21]
	v_mul_f32_e32 v95, v117, v117
	s_waitcnt lgkmcnt(0)
	v_mul_f32_e32 v100, v119, v119
	v_fmac_f32_e32 v95, v116, v116
	v_fmac_f32_e32 v100, v118, v118
	v_add_f32_e32 v95, v95, v100
	v_mul_f32_e32 v100, v113, v113
	v_fmac_f32_e32 v100, v112, v112
	v_add_f32_e32 v95, v95, v100
	v_mul_f32_e32 v100, v115, v115
	v_fmac_f32_e32 v100, v114, v114
	v_add_f32_e32 v95, v100, v95
	v_mov_b32_e32 v100, v95
	s_nop 1
	v_permlane16_swap_b32_e32 v100, v95
	s_waitcnt lgkmcnt(0)
	v_add_f32_e32 v95, v95, v100
	v_mov_b32_e32 v100, v95
	s_nop 1
	v_permlane32_swap_b32_e32 v100, v95
	s_and_saveexec_b64 s[20:21], s[8:9]
	s_cbranch_execz .LBB0_242
	s_waitcnt lgkmcnt(0)
	v_add_f32_e32 v95, v95, v100
	ds_write_b32 v93, v95 offset:528
.LBB0_242:
	s_or_b64 exec, exec, s[20:21]
	v_mul_f32_e32 v95, v97, v97
	s_waitcnt lgkmcnt(0)
	v_mul_f32_e32 v100, v99, v99
	v_fmac_f32_e32 v95, v96, v96
	v_fmac_f32_e32 v100, v98, v98
	v_add_f32_e32 v95, v95, v100
	v_mul_f32_e32 v100, v89, v89
	v_fmac_f32_e32 v100, v88, v88
	v_add_f32_e32 v95, v95, v100
	v_mul_f32_e32 v100, v91, v91
	v_fmac_f32_e32 v100, v90, v90
	v_add_f32_e32 v95, v100, v95
	v_mov_b32_e32 v100, v95
	s_nop 1
	v_permlane16_swap_b32_e32 v100, v95
	s_waitcnt lgkmcnt(0)
	v_add_f32_e32 v95, v95, v100
	v_mov_b32_e32 v100, v95
	s_nop 1
	v_permlane32_swap_b32_e32 v100, v95
	s_and_saveexec_b64 s[20:21], s[8:9]
	s_cbranch_execz .LBB0_244
	s_waitcnt lgkmcnt(0)
	v_add_f32_e32 v95, v95, v100
	ds_write_b32 v93, v95 offset:1024
.LBB0_244:
	s_or_b64 exec, exec, s[20:21]
	v_mul_f32_e32 v95, v85, v85
	s_waitcnt lgkmcnt(0)
	v_mul_f32_e32 v100, v87, v87
	v_fmac_f32_e32 v95, v84, v84
	v_fmac_f32_e32 v100, v86, v86
	v_add_f32_e32 v95, v95, v100
	v_mul_f32_e32 v100, v81, v81
	v_fmac_f32_e32 v100, v80, v80
	v_add_f32_e32 v95, v95, v100
	v_mul_f32_e32 v100, v83, v83
	v_fmac_f32_e32 v100, v82, v82
	v_add_f32_e32 v95, v100, v95
	v_mov_b32_e32 v100, v95
	s_nop 1
	v_permlane16_swap_b32_e32 v100, v95
	s_waitcnt lgkmcnt(0)
	v_add_f32_e32 v95, v95, v100
	v_mov_b32_e32 v100, v95
	s_nop 1
	v_permlane32_swap_b32_e32 v100, v95
	s_and_saveexec_b64 s[20:21], s[8:9]
	s_cbranch_execz .LBB0_246
	s_waitcnt lgkmcnt(0)
	v_add_f32_e32 v95, v95, v100
	ds_write_b32 v93, v95 offset:1040
.LBB0_246:
	s_or_b64 exec, exec, s[20:21]
	v_mul_f32_e32 v95, v77, v77
	s_waitcnt lgkmcnt(0)
	v_mul_f32_e32 v100, v79, v79
	v_fmac_f32_e32 v95, v76, v76
	v_fmac_f32_e32 v100, v78, v78
	v_add_f32_e32 v95, v95, v100
	v_mul_f32_e32 v100, v73, v73
	v_fmac_f32_e32 v100, v72, v72
	v_add_f32_e32 v95, v95, v100
	v_mul_f32_e32 v100, v75, v75
	v_fmac_f32_e32 v100, v74, v74
	v_add_f32_e32 v95, v100, v95
	v_mov_b32_e32 v100, v95
	s_nop 1
	v_permlane16_swap_b32_e32 v100, v95
	s_waitcnt lgkmcnt(0)
	v_add_f32_e32 v95, v95, v100
	v_mov_b32_e32 v100, v95
	s_nop 1
	v_permlane32_swap_b32_e32 v100, v95
	s_and_saveexec_b64 s[20:21], s[8:9]
	s_cbranch_execz .LBB0_248
	s_waitcnt lgkmcnt(0)
	v_add_f32_e32 v95, v95, v100
	ds_write_b32 v93, v95 offset:1536
; #define LAS __attribute__((address_space(3)))
; #define EPI_BAR() do { asm volatile("s_waitcnt lgkmcnt(0)" ::: "memory"); __builtin_amdgcn_s_barrier(); asm volatile("" ::: "memory"); } while (0)
; __device__ __forceinline__ void head_ss(const f32x4 (&v)[2][2][4][2], float (&tot)[2][4][2], LAS float* X, int wr, int wc, int fr, int fq) {
; #pragma unroll
;     for (int ai = 0; ai < 2; ++ai)
; #pragma unroll
;         for (int m = 0; m < 4; ++m)
; #pragma unroll
;             for (int bj = 0; bj < 2; ++bj) {
;                 const f32x4 a = v[ai][bj][m][0], b = v[ai][bj][m][1];
;                 float s = (a[0] * a[0] + a[1] * a[1]) + (a[2] * a[2] + a[3] * a[3]) + (b[0] * b[0] + b[1] * b[1]) + (b[2] * b[2] + b[3] * b[3]);
;                 s += __shfl_xor(s, 16); s += __shfl_xor(s, 32);
;                 if (fq == 0) X[((ai * 128 + wr * 64 + m * 16 + fr) * 2 + bj) * 4 + wc] = s;
;             }
;     EPI_BAR();
.LBB0_248:
	s_or_b64 exec, exec, s[20:21]
	v_mul_f32_e32 v95, v69, v69
	s_waitcnt lgkmcnt(0)
	v_mul_f32_e32 v100, v71, v71
	v_fmac_f32_e32 v95, v68, v68
	v_fmac_f32_e32 v100, v70, v70
	v_add_f32_e32 v95, v95, v100
	v_mul_f32_e32 v100, v65, v65
	v_fmac_f32_e32 v100, v64, v64
	v_add_f32_e32 v95, v95, v100
	v_mul_f32_e32 v100, v67, v67
	v_fmac_f32_e32 v100, v66, v66
	v_add_f32_e32 v95, v100, v95
	v_mov_b32_e32 v100, v95
	s_nop 1
	v_permlane16_swap_b32_e32 v100, v95
	s_waitcnt lgkmcnt(0)
	v_add_f32_e32 v95, v95, v100
	v_mov_b32_e32 v100, v95
	s_nop 1
	v_permlane32_swap_b32_e32 v100, v95
	s_and_saveexec_b64 s[20:21], s[8:9]
	s_cbranch_execz .LBB0_250
	s_waitcnt lgkmcnt(0)
	v_add_f32_e32 v95, v95, v100
	ds_write_b32 v93, v95 offset:1552
.LBB0_250:
	s_or_b64 exec, exec, s[20:21]
	v_mul_f32_e32 v95, v61, v61
	s_waitcnt lgkmcnt(0)
	v_mul_f32_e32 v100, v63, v63
	v_fmac_f32_e32 v95, v60, v60
	v_fmac_f32_e32 v100, v62, v62
	v_add_f32_e32 v95, v95, v100
	v_mul_f32_e32 v100, v57, v57
	v_fmac_f32_e32 v100, v56, v56
	v_add_f32_e32 v95, v95, v100
	v_mul_f32_e32 v100, v59, v59
	v_fmac_f32_e32 v100, v58, v58
	v_add_f32_e32 v95, v100, v95
	v_mov_b32_e32 v100, v95
	s_nop 1
	v_permlane16_swap_b32_e32 v100, v95
	s_waitcnt lgkmcnt(0)
	v_add_f32_e32 v95, v95, v100
	v_mov_b32_e32 v100, v95
	s_nop 1
	v_permlane32_swap_b32_e32 v100, v95
	s_and_saveexec_b64 s[20:21], s[8:9]
	s_cbranch_execz .LBB0_252
	s_waitcnt lgkmcnt(0)
	v_add_f32_e32 v95, v95, v100
	ds_write_b32 v93, v95 offset:4096
.LBB0_252:
	s_or_b64 exec, exec, s[20:21]
	v_mul_f32_e32 v95, v53, v53
	s_waitcnt lgkmcnt(0)
	v_mul_f32_e32 v100, v55, v55
	v_fmac_f32_e32 v95, v52, v52
	v_fmac_f32_e32 v100, v54, v54
	v_add_f32_e32 v95, v95, v100
	v_mul_f32_e32 v100, v49, v49
	v_fmac_f32_e32 v100, v48, v48
	v_add_f32_e32 v95, v95, v100
	v_mul_f32_e32 v100, v51, v51
	v_fmac_f32_e32 v100, v50, v50
	v_add_f32_e32 v95, v100, v95
	v_mov_b32_e32 v100, v95
	s_nop 1
	v_permlane16_swap_b32_e32 v100, v95
	s_waitcnt lgkmcnt(0)
	v_add_f32_e32 v95, v95, v100
	v_mov_b32_e32 v100, v95
	s_nop 1
	v_permlane32_swap_b32_e32 v100, v95
	s_and_saveexec_b64 s[20:21], s[8:9]
	s_cbranch_execz .LBB0_254
	s_waitcnt lgkmcnt(0)
	v_add_f32_e32 v95, v95, v100
	ds_write_b32 v93, v95 offset:4112
.LBB0_254:
	s_or_b64 exec, exec, s[20:21]
	v_mul_f32_e32 v95, v45, v45
	s_waitcnt lgkmcnt(0)
	v_mul_f32_e32 v100, v47, v47
	v_fmac_f32_e32 v95, v44, v44
	v_fmac_f32_e32 v100, v46, v46
	v_add_f32_e32 v95, v95, v100
	v_mul_f32_e32 v100, v41, v41
	v_fmac_f32_e32 v100, v40, v40
	v_add_f32_e32 v95, v95, v100
	v_mul_f32_e32 v100, v43, v43
	v_fmac_f32_e32 v100, v42, v42
	v_add_f32_e32 v95, v100, v95
	v_mov_b32_e32 v100, v95
	s_nop 1
	v_permlane16_swap_b32_e32 v100, v95
	s_waitcnt lgkmcnt(0)
	v_add_f32_e32 v95, v95, v100
	v_mov_b32_e32 v100, v95
	s_nop 1
	v_permlane32_swap_b32_e32 v100, v95
	s_and_saveexec_b64 s[20:21], s[8:9]
	s_cbranch_execz .LBB0_256
	s_waitcnt lgkmcnt(0)
	v_add_f32_e32 v95, v95, v100
	ds_write_b32 v93, v95 offset:4608
.LBB0_256:
	s_or_b64 exec, exec, s[20:21]
	v_mul_f32_e32 v95, v37, v37
	s_waitcnt lgkmcnt(0)
	v_mul_f32_e32 v100, v39, v39
	v_fmac_f32_e32 v95, v36, v36
	v_fmac_f32_e32 v100, v38, v38
	v_add_f32_e32 v95, v95, v100
	v_mul_f32_e32 v100, v33, v33
	v_fmac_f32_e32 v100, v32, v32
	v_add_f32_e32 v95, v95, v100
	v_mul_f32_e32 v100, v35, v35
	v_fmac_f32_e32 v100, v34, v34
	v_add_f32_e32 v95, v100, v95
	v_mov_b32_e32 v100, v95
	s_nop 1
	v_permlane16_swap_b32_e32 v100, v95
	s_waitcnt lgkmcnt(0)
	v_add_f32_e32 v95, v95, v100
	v_mov_b32_e32 v100, v95
	s_nop 1
	v_permlane32_swap_b32_e32 v100, v95
	s_and_saveexec_b64 s[20:21], s[8:9]
	s_cbranch_execz .LBB0_258
	s_waitcnt lgkmcnt(0)
	v_add_f32_e32 v95, v95, v100
	ds_write_b32 v93, v95 offset:4624
.LBB0_258:
	s_or_b64 exec, exec, s[20:21]
	v_mul_f32_e32 v95, v29, v29
	s_waitcnt lgkmcnt(0)
	v_mul_f32_e32 v100, v31, v31
	v_fmac_f32_e32 v95, v28, v28
	v_fmac_f32_e32 v100, v30, v30
	v_add_f32_e32 v95, v95, v100
	v_mul_f32_e32 v100, v25, v25
	v_fmac_f32_e32 v100, v24, v24
	v_add_f32_e32 v95, v95, v100
	v_mul_f32_e32 v100, v27, v27
	v_fmac_f32_e32 v100, v26, v26
	v_add_f32_e32 v95, v100, v95
	v_mov_b32_e32 v100, v95
	s_nop 1
	v_permlane16_swap_b32_e32 v100, v95
	s_waitcnt lgkmcnt(0)
	v_add_f32_e32 v95, v95, v100
	v_mov_b32_e32 v100, v95
	s_nop 1
	v_permlane32_swap_b32_e32 v100, v95
	s_and_saveexec_b64 s[20:21], s[8:9]
	s_cbranch_execz .LBB0_260
	s_waitcnt lgkmcnt(0)
	v_add_f32_e32 v95, v95, v100
	ds_write_b32 v93, v95 offset:5120
.LBB0_260:
	s_or_b64 exec, exec, s[20:21]
	v_mul_f32_e32 v95, v21, v21
	s_waitcnt lgkmcnt(0)
	v_mul_f32_e32 v100, v23, v23
	v_fmac_f32_e32 v95, v20, v20
	v_fmac_f32_e32 v100, v22, v22
	v_add_f32_e32 v95, v95, v100
	v_mul_f32_e32 v100, v17, v17
	v_fmac_f32_e32 v100, v16, v16
	v_add_f32_e32 v95, v95, v100
	v_mul_f32_e32 v100, v19, v19
	v_fmac_f32_e32 v100, v18, v18
	v_add_f32_e32 v95, v100, v95
	v_mov_b32_e32 v100, v95
	s_nop 1
	v_permlane16_swap_b32_e32 v100, v95
	s_waitcnt lgkmcnt(0)
	v_add_f32_e32 v95, v95, v100
	v_mov_b32_e32 v100, v95
	s_nop 1
	v_permlane32_swap_b32_e32 v100, v95
	s_and_saveexec_b64 s[20:21], s[8:9]
	s_cbranch_execz .LBB0_262
	s_waitcnt lgkmcnt(0)
	v_add_f32_e32 v95, v95, v100
	ds_write_b32 v93, v95 offset:5136
.LBB0_262:
	s_or_b64 exec, exec, s[20:21]
	v_mul_f32_e32 v95, v13, v13
	s_waitcnt lgkmcnt(0)
	v_mul_f32_e32 v100, v15, v15
	v_fmac_f32_e32 v95, v12, v12
	v_fmac_f32_e32 v100, v14, v14
	v_add_f32_e32 v95, v95, v100
	v_mul_f32_e32 v100, v9, v9
	v_fmac_f32_e32 v100, v8, v8
	v_add_f32_e32 v95, v95, v100
	v_mul_f32_e32 v100, v11, v11
	v_fmac_f32_e32 v100, v10, v10
	v_add_f32_e32 v95, v100, v95
	v_mov_b32_e32 v100, v95
	s_nop 1
	v_permlane16_swap_b32_e32 v100, v95
	s_waitcnt lgkmcnt(0)
	v_add_f32_e32 v95, v95, v100
	v_mov_b32_e32 v100, v95
	s_nop 1
	v_permlane32_swap_b32_e32 v100, v95
	s_and_saveexec_b64 s[20:21], s[8:9]
	s_cbranch_execz .LBB0_264
	s_waitcnt lgkmcnt(0)
	v_add_f32_e32 v95, v95, v100
	ds_write_b32 v93, v95 offset:5632
.LBB0_264:
	s_or_b64 exec, exec, s[20:21]
	v_mul_f32_e32 v95, v5, v5
	s_waitcnt lgkmcnt(0)
	v_mul_f32_e32 v100, v7, v7
	v_fmac_f32_e32 v95, v4, v4
	v_fmac_f32_e32 v100, v6, v6
	v_add_f32_e32 v95, v95, v100
	v_mul_f32_e32 v100, v1, v1
	v_fmac_f32_e32 v100, v0, v0
	v_add_f32_e32 v95, v95, v100
	v_mul_f32_e32 v100, v3, v3
	v_fmac_f32_e32 v100, v2, v2
	v_add_f32_e32 v95, v100, v95
	v_mov_b32_e32 v92, v95
	s_nop 1
	v_permlane16_swap_b32_e32 v92, v95
	s_waitcnt lgkmcnt(0)
	v_add_f32_e32 v92, v95, v92
	v_mov_b32_e32 v94, v92
	s_nop 1
	v_permlane32_swap_b32_e32 v94, v92
	s_and_saveexec_b64 s[20:21], s[8:9]
	s_cbranch_execz .LBB0_266
	s_waitcnt lgkmcnt(0)
	v_add_f32_e32 v92, v92, v94
	ds_write_b32 v93, v92 offset:5648

; __device__ __forceinline__ u32x4 pack8(f32x4 a, f32x4 b) { u32x4 w; w.x = cvtpk(a[0], a[1]); w.y = cvtpk(a[2], a[3]); w.z = cvtpk(b[0], b[1]); w.w = cvtpk(b[2], b[3]); return w; }
; #define FOR_BJ _Pragma("unroll") for (int bj = 0; bj < 2; ++bj)
;     __device__ __forceinline__ void operator()(f32x4 (&acc)[2][2][4][2], const Unit& u, int wr, int wc, int fr, int fq) const {
;         const float* xb = u.pm < NPR / BM ? xp : xs - (size_t)NPR * DM;
; #pragma unroll
;         for (int ai = 0; ai < 2; ++ai) {
;             f32x4 xr[4][2][2];
; #pragma unroll
;             for (int m = 0; m < 4; ++m) FOR_BJ { const unsigned off = (unsigned)(u.pm * BM + ai * HALF + wr * 64 + m * 16 + fr) * DM + u.pn * BM + 128 * bj + 32 * wc + 8 * fq;
;                 xr[m][bj][0] = *(const f32x4*)(xb + off); xr[m][bj][1] = *(const f32x4*)(xb + off + 4); }
; #pragma unroll
;             for (int m = 0; m < 4; ++m) FOR_BJ { const unsigned off = (unsigned)(u.pm * BM + ai * HALF + wr * 64 + m * 16 + fr) * DM + u.pn * BM + 128 * bj + 32 * wc + 8 * fq;
;                 const f32x4 v0 = acc[ai][bj][m][0] + xr[m][bj][0], v1 = acc[ai][bj][m][1] + xr[m][bj][1];
;                 acc[ai][bj][m][0] = v0; acc[ai][bj][m][1] = v1;
;                 *(u32x4*)(HB + off) = pack8(v0, v1); }
;             asm volatile("" ::: "memory");
.LBB0_759:
	v_readlane_b32 s36, v243, 3
	s_cmpk_lt_i32 s30, 0x80
	v_readlane_b32 s37, v243, 4
	v_readlane_b32 s50, v243, 17
	v_readlane_b32 s51, v243, 18
	v_lshl_add_u32 v142, s30, 8, v152
	v_lshl_or_b32 v136, s10, 8, v154
	s_cselect_b32 s51, s37, s62
	s_cselect_b32 s50, s36, s61
	v_lshl_add_u32 v136, v142, 11, v136
	s_waitcnt vmcnt(0)
	v_lshl_add_u64 v[148:149], v[136:137], 2, s[50:51]
	global_load_dwordx4 v[144:147], v[148:149], off
	global_load_dwordx4 v[160:163], v[148:149], off offset:16
	global_load_dwordx4 v[164:167], v[148:149], off offset:512
	global_load_dwordx4 v[168:171], v[148:149], off offset:528
	v_mov_b32_e32 v149, v137
	v_add_u32_e32 v148, 0x8000, v136
	v_lshl_add_u64 v[150:151], v[148:149], 2, s[50:51]
	global_load_dwordx4 v[172:175], v[150:151], off
	global_load_dwordx4 v[180:183], v[150:151], off offset:16
	global_load_dwordx4 v[184:187], v[150:151], off offset:528
	global_load_dwordx4 v[188:191], v[150:151], off offset:512
	v_mov_b32_e32 v225, v137
	v_add_u32_e32 v224, 0x10000, v136
	v_lshl_add_u64 v[150:151], v[224:225], 2, s[50:51]
	global_load_dwordx4 v[192:195], v[150:151], off
	global_load_dwordx4 v[196:199], v[150:151], off offset:16
	global_load_dwordx4 v[200:203], v[150:151], off offset:512
	global_load_dwordx4 v[204:207], v[150:151], off offset:528
	v_mov_b32_e32 v227, v137
	v_add_u32_e32 v226, 0x18000, v136
	v_lshl_add_u64 v[150:151], v[226:227], 2, s[50:51]
	global_load_dwordx4 v[208:211], v[150:151], off
	global_load_dwordx4 v[212:215], v[150:151], off offset:16
	global_load_dwordx4 v[216:219], v[150:151], off offset:512
	global_load_dwordx4 v[220:223], v[150:151], off offset:528
	v_mov_b32_e32 v151, v137
	v_add_u32_e32 v150, 0x8080, v136
	v_lshl_add_u64 v[236:237], v[148:149], 1, s[88:89]
	v_lshl_add_u64 v[238:239], v[150:151], 1, s[88:89]
	v_mov_b32_e32 v229, v137
	v_or_b32_e32 v228, 0x80, v136
	v_lshl_add_u64 v[234:235], v[136:137], 1, s[88:89]
	v_lshl_add_u64 v[228:229], v[228:229], 1, s[88:89]
	v_mov_b32_e32 v231, v137
	v_add_u32_e32 v230, 0x10080, v136
	v_mov_b32_e32 v233, v137
	v_add_u32_e32 v232, 0x18080, v136
	v_readlane_b32 s46, v243, 13
	v_readlane_b32 s47, v243, 14
	v_readlane_b32 s38, v243, 5
	v_readlane_b32 s39, v243, 6
	v_readlane_b32 s40, v243, 7
	v_readlane_b32 s41, v243, 8
	v_readlane_b32 s42, v243, 9
	v_readlane_b32 s43, v243, 10
	v_readlane_b32 s44, v243, 11
	v_readlane_b32 s45, v243, 12
	v_readlane_b32 s48, v243, 15
	v_readlane_b32 s49, v243, 16
	s_waitcnt vmcnt(0)
	v_pk_add_f32 v[148:149], v[126:127], v[146:147]
	v_pk_add_f32 v[150:151], v[124:125], v[144:145]
	v_pk_add_f32 v[144:145], v[122:123], v[162:163]
	v_pk_add_f32 v[146:147], v[120:121], v[160:161]
	v_pk_add_f32 v[118:119], v[118:119], v[174:175]
	v_pk_add_f32 v[116:117], v[116:117], v[172:173]
	v_pk_add_f32 v[114:115], v[114:115], v[182:183]
	v_pk_add_f32 v[112:113], v[112:113], v[180:181]
	v_pk_add_f32 v[124:125], v[110:111], v[166:167]
	v_pk_add_f32 v[126:127], v[108:109], v[164:165]
	v_pk_add_f32 v[120:121], v[106:107], v[170:171]
	v_pk_add_f32 v[122:123], v[104:105], v[168:169]
	v_cvt_pk_bf16_f32 v160, v150, v151
	v_cvt_pk_bf16_f32 v161, v148, v149
	v_cvt_pk_bf16_f32 v162, v146, v147
	v_cvt_pk_bf16_f32 v163, v144, v145
	v_pk_add_f32 v[108:109], v[94:95], v[190:191]
	v_pk_add_f32 v[110:111], v[92:93], v[188:189]
	v_pk_add_f32 v[104:105], v[90:91], v[186:187]
	v_pk_add_f32 v[106:107], v[88:89], v[184:185]
	v_pk_add_f32 v[90:91], v[102:103], v[194:195]
	v_pk_add_f32 v[94:95], v[100:101], v[192:193]
	v_pk_add_f32 v[88:89], v[98:99], v[198:199]
	v_pk_add_f32 v[92:93], v[96:97], v[196:197]
	v_cvt_pk_bf16_f32 v96, v116, v117
	v_cvt_pk_bf16_f32 v97, v118, v119
	v_cvt_pk_bf16_f32 v98, v112, v113
	v_cvt_pk_bf16_f32 v99, v114, v115
	v_cvt_pk_bf16_f32 v164, v126, v127
	v_cvt_pk_bf16_f32 v165, v124, v125
	v_cvt_pk_bf16_f32 v166, v122, v123
	v_cvt_pk_bf16_f32 v167, v120, v121
	global_store_dwordx4 v[234:235], v[160:163], off
	global_store_dwordx4 v[228:229], v[164:167], off
	v_cvt_pk_bf16_f32 v100, v110, v111
	v_cvt_pk_bf16_f32 v101, v108, v109
	v_cvt_pk_bf16_f32 v102, v106, v107
	v_cvt_pk_bf16_f32 v103, v104, v105
	v_cvt_pk_bf16_f32 v160, v94, v95
	v_cvt_pk_bf16_f32 v161, v90, v91
	global_store_dwordx4 v[236:237], v[96:99], off
	global_store_dwordx4 v[238:239], v[100:103], off
	v_cvt_pk_bf16_f32 v162, v92, v93
	v_cvt_pk_bf16_f32 v163, v88, v89
	v_lshl_add_u64 v[96:97], v[224:225], 1, s[88:89]
	global_store_dwordx4 v[96:97], v[160:163], off
	v_pk_add_f32 v[96:97], v[82:83], v[202:203]
	v_pk_add_f32 v[100:101], v[80:81], v[200:201]
	v_pk_add_f32 v[80:81], v[74:75], v[206:207]
	v_pk_add_f32 v[98:99], v[72:73], v[204:205]
	v_cvt_pk_bf16_f32 v72, v100, v101
	v_cvt_pk_bf16_f32 v73, v96, v97
	v_cvt_pk_bf16_f32 v74, v98, v99
	v_cvt_pk_bf16_f32 v75, v80, v81
	v_lshl_add_u64 v[82:83], v[230:231], 1, s[88:89]
	global_store_dwordx4 v[82:83], v[72:75], off
	v_pk_add_f32 v[82:83], v[84:85], v[208:209]
	v_pk_add_f32 v[76:77], v[76:77], v[212:213]
	v_pk_add_f32 v[74:75], v[86:87], v[210:211]
	v_pk_add_f32 v[72:73], v[78:79], v[214:215]
	v_cvt_pk_bf16_f32 v84, v82, v83
	v_cvt_pk_bf16_f32 v85, v74, v75
	v_cvt_pk_bf16_f32 v86, v76, v77
	v_cvt_pk_bf16_f32 v87, v72, v73
	v_lshl_add_u64 v[78:79], v[226:227], 1, s[88:89]
	v_pk_add_f32 v[70:71], v[70:71], v[218:219]
	v_pk_add_f32 v[68:69], v[68:69], v[216:217]
	v_pk_add_f32 v[66:67], v[66:67], v[222:223]
	v_pk_add_f32 v[64:65], v[64:65], v[220:221]
	global_store_dwordx4 v[78:79], v[84:87], off
	v_lshl_add_u64 v[78:79], v[232:233], 1, s[88:89]
	v_add_u32_e32 v224, 0x48000, v136
	v_cvt_pk_bf16_f32 v84, v68, v69
	v_cvt_pk_bf16_f32 v85, v70, v71
	v_cvt_pk_bf16_f32 v86, v64, v65
	v_cvt_pk_bf16_f32 v87, v66, v67
; #define LAS __attribute__((address_space(3)))
; __device__ __forceinline__ u32x4 pack8(f32x4 a, f32x4 b) { u32x4 w; w.x = cvtpk(a[0], a[1]); w.y = cvtpk(a[2], a[3]); w.z = cvtpk(b[0], b[1]); w.w = cvtpk(b[2], b[3]); return w; }
; #define EPI_BAR() do { asm volatile("s_waitcnt lgkmcnt(0)" ::: "memory"); __builtin_amdgcn_s_barrier(); asm volatile("" ::: "memory"); } while (0)
; #define FOR_BJ _Pragma("unroll") for (int bj = 0; bj < 2; ++bj)
; __device__ __forceinline__ void head_ss(const f32x4 (&v)[2][2][4][2], float (&tot)[2][4][2], LAS float* X, int wr, int wc, int fr, int fq) {
; #pragma unroll
;     for (int ai = 0; ai < 2; ++ai)
; #pragma unroll
;         for (int m = 0; m < 4; ++m)
; #pragma unroll
;             for (int bj = 0; bj < 2; ++bj) {
;                 const f32x4 a = v[ai][bj][m][0], b = v[ai][bj][m][1];
;                 float s = (a[0] * a[0] + a[1] * a[1]) + (a[2] * a[2] + a[3] * a[3]) + (b[0] * b[0] + b[1] * b[1]) + (b[2] * b[2] + b[3] * b[3]);
;                 s += __shfl_xor(s, 16); s += __shfl_xor(s, 32);
;                 if (fq == 0) X[((ai * 128 + wr * 64 + m * 16 + fr) * 2 + bj) * 4 + wc] = s;
;             }
;     EPI_BAR();
;     __device__ __forceinline__ void operator()(f32x4 (&acc)[2][2][4][2], const Unit& u, int wr, int wc, int fr, int fq) const {
;         const float* xb = u.pm < NPR / BM ? xp : xs - (size_t)NPR * DM;
; #pragma unroll
;         for (int ai = 0; ai < 2; ++ai) {
;             f32x4 xr[4][2][2];
; #pragma unroll
;             for (int m = 0; m < 4; ++m) FOR_BJ { const unsigned off = (unsigned)(u.pm * BM + ai * HALF + wr * 64 + m * 16 + fr) * DM + u.pn * BM + 128 * bj + 32 * wc + 8 * fq;
;                 xr[m][bj][0] = *(const f32x4*)(xb + off); xr[m][bj][1] = *(const f32x4*)(xb + off + 4); }
; #pragma unroll
;             for (int m = 0; m < 4; ++m) FOR_BJ { const unsigned off = (unsigned)(u.pm * BM + ai * HALF + wr * 64 + m * 16 + fr) * DM + u.pn * BM + 128 * bj + 32 * wc + 8 * fq;
;                 const f32x4 v0 = acc[ai][bj][m][0] + xr[m][bj][0], v1 = acc[ai][bj][m][1] + xr[m][bj][1];
;                 acc[ai][bj][m][0] = v0; acc[ai][bj][m][1] = v1;
;                 *(u32x4*)(HB + off) = pack8(v0, v1); }
;             asm volatile("" ::: "memory");
;         }
;         float tot[2][4][2]; head_ss(acc, tot, X, wr, wc, fr, fq);
	global_store_dwordx4 v[78:79], v[84:87], off
	v_add_u32_e32 v78, 0x40000, v136
	v_mov_b32_e32 v79, v137
	v_lshl_add_u64 v[102:103], v[78:79], 2, s[50:51]
	global_load_dwordx4 v[84:87], v[102:103], off
	global_load_dwordx4 v[160:163], v[102:103], off offset:16
	global_load_dwordx4 v[164:167], v[102:103], off offset:512
	global_load_dwordx4 v[168:171], v[102:103], off offset:528
	v_lshl_add_u64 v[102:103], v[224:225], 2, s[50:51]
	global_load_dwordx4 v[172:175], v[102:103], off
	global_load_dwordx4 v[180:183], v[102:103], off offset:16
	global_load_dwordx4 v[184:187], v[102:103], off offset:512
	global_load_dwordx4 v[188:191], v[102:103], off offset:528
	v_add_u32_e32 v226, 0x50000, v136
	v_lshl_add_u64 v[102:103], v[226:227], 2, s[50:51]
	global_load_dwordx4 v[192:195], v[102:103], off
	global_load_dwordx4 v[196:199], v[102:103], off offset:16
	global_load_dwordx4 v[200:203], v[102:103], off offset:512
	global_load_dwordx4 v[204:207], v[102:103], off offset:528
	v_mov_b32_e32 v229, v137
	v_add_u32_e32 v228, 0x58000, v136
	v_lshl_add_u64 v[102:103], v[228:229], 2, s[50:51]
	global_load_dwordx4 v[208:211], v[102:103], off
	global_load_dwordx4 v[212:215], v[102:103], off offset:16
	global_load_dwordx4 v[216:219], v[102:103], off offset:512
	global_load_dwordx4 v[220:223], v[102:103], off offset:528
	v_lshl_add_u64 v[236:237], v[78:79], 1, s[88:89]
	v_add_u32_e32 v230, 0x40080, v136
	v_add_u32_e32 v232, 0x48080, v136
	v_mov_b32_e32 v235, v137
	v_add_u32_e32 v234, 0x50080, v136
	v_add_u32_e32 v136, 0x58080, v136
	s_waitcnt vmcnt(15)
	v_pk_add_f32 v[86:87], v[62:63], v[86:87]
	v_pk_add_f32 v[102:103], v[60:61], v[84:85]
	s_waitcnt vmcnt(14)
	v_pk_add_f32 v[78:79], v[58:59], v[162:163]
	v_pk_add_f32 v[84:85], v[56:57], v[160:161]
	s_waitcnt vmcnt(13)
	v_pk_add_f32 v[54:55], v[54:55], v[166:167]
	v_pk_add_f32 v[62:63], v[52:53], v[164:165]
	s_waitcnt vmcnt(12)
	v_pk_add_f32 v[52:53], v[46:47], v[170:171]
	v_pk_add_f32 v[58:59], v[44:45], v[168:169]
	v_cvt_pk_bf16_f32 v44, v102, v103
	v_cvt_pk_bf16_f32 v45, v86, v87
	v_cvt_pk_bf16_f32 v46, v84, v85
	v_cvt_pk_bf16_f32 v47, v78, v79
	global_store_dwordx4 v[236:237], v[44:47], off
	v_lshl_add_u64 v[56:57], v[230:231], 1, s[88:89]
	s_waitcnt vmcnt(12)
	v_pk_add_f32 v[50:51], v[50:51], v[174:175]
	v_cvt_pk_bf16_f32 v44, v62, v63
	v_cvt_pk_bf16_f32 v45, v54, v55
	v_cvt_pk_bf16_f32 v46, v58, v59
	v_cvt_pk_bf16_f32 v47, v52, v53
	global_store_dwordx4 v[56:57], v[44:47], off
	v_pk_add_f32 v[60:61], v[48:49], v[172:173]
	s_waitcnt vmcnt(12)
	v_pk_add_f32 v[56:57], v[40:41], v[180:181]
	v_pk_add_f32 v[46:47], v[42:43], v[182:183]
	v_cvt_pk_bf16_f32 v40, v60, v61
	v_cvt_pk_bf16_f32 v41, v50, v51
	v_cvt_pk_bf16_f32 v42, v56, v57
	v_cvt_pk_bf16_f32 v43, v46, v47
	v_lshl_add_u64 v[44:45], v[224:225], 1, s[88:89]
	global_store_dwordx4 v[44:45], v[40:43], off
	s_waitcnt vmcnt(12)
	v_pk_add_f32 v[48:49], v[32:33], v[184:185]
	s_waitcnt vmcnt(11)
	v_pk_add_f32 v[44:45], v[24:25], v[188:189]
	v_pk_add_f32 v[42:43], v[34:35], v[186:187]
	v_pk_add_f32 v[40:41], v[26:27], v[190:191]
	v_cvt_pk_bf16_f32 v24, v48, v49
	v_cvt_pk_bf16_f32 v25, v42, v43
	v_cvt_pk_bf16_f32 v26, v44, v45
	v_cvt_pk_bf16_f32 v27, v40, v41
	v_lshl_add_u64 v[32:33], v[232:233], 1, s[88:89]
	global_store_dwordx4 v[32:33], v[24:27], off
	s_waitcnt vmcnt(11)
	v_pk_add_f32 v[32:33], v[38:39], v[194:195]
	v_pk_add_f32 v[36:37], v[36:37], v[192:193]
	s_waitcnt vmcnt(10)
	v_pk_add_f32 v[30:31], v[30:31], v[198:199]
	v_pk_add_f32 v[34:35], v[28:29], v[196:197]
	v_cvt_pk_bf16_f32 v24, v36, v37
	v_cvt_pk_bf16_f32 v25, v32, v33
	v_cvt_pk_bf16_f32 v26, v34, v35
	v_cvt_pk_bf16_f32 v27, v30, v31
	v_lshl_add_u64 v[28:29], v[226:227], 1, s[88:89]
	global_store_dwordx4 v[28:29], v[24:27], off
	s_waitcnt vmcnt(10)
	v_pk_add_f32 v[28:29], v[16:17], v[200:201]
	s_waitcnt vmcnt(9)
	v_pk_add_f32 v[16:17], v[10:11], v[206:207]
	v_pk_add_f32 v[24:25], v[18:19], v[202:203]
	v_pk_add_f32 v[26:27], v[8:9], v[204:205]
	v_cvt_pk_bf16_f32 v8, v28, v29
	v_cvt_pk_bf16_f32 v9, v24, v25
	v_cvt_pk_bf16_f32 v10, v26, v27
	v_cvt_pk_bf16_f32 v11, v16, v17
	v_lshl_add_u64 v[18:19], v[234:235], 1, s[88:89]
	global_store_dwordx4 v[18:19], v[8:11], off
	s_waitcnt vmcnt(9)
	v_pk_add_f32 v[18:19], v[20:21], v[208:209]
	s_waitcnt vmcnt(8)
	v_pk_add_f32 v[12:13], v[12:13], v[212:213]
	v_pk_add_f32 v[10:11], v[22:23], v[210:211]
	v_pk_add_f32 v[8:9], v[14:15], v[214:215]
	v_cvt_pk_bf16_f32 v20, v18, v19
	v_cvt_pk_bf16_f32 v21, v10, v11
	v_cvt_pk_bf16_f32 v22, v12, v13
	v_cvt_pk_bf16_f32 v23, v8, v9
	v_lshl_add_u64 v[14:15], v[228:229], 1, s[88:89]
	s_waitcnt vmcnt(7)
	v_pk_add_f32 v[6:7], v[6:7], v[218:219]
	v_pk_add_f32 v[4:5], v[4:5], v[216:217]
	s_waitcnt vmcnt(6)
	v_pk_add_f32 v[2:3], v[2:3], v[222:223]
	v_pk_add_f32 v[0:1], v[0:1], v[220:221]
	global_store_dwordx4 v[14:15], v[20:23], off
	v_lshl_add_u64 v[14:15], v[136:137], 1, s[88:89]
	s_nop 0
	v_cvt_pk_bf16_f32 v20, v4, v5
	v_cvt_pk_bf16_f32 v21, v6, v7
	v_cvt_pk_bf16_f32 v22, v0, v1
	v_cvt_pk_bf16_f32 v23, v2, v3
	global_store_dwordx4 v[14:15], v[20:23], off
	v_and_b32_e32 v15, 64, v159
	v_xor_b32_e32 v14, 16, v159
	v_mul_f32_e32 v20, v151, v151
	v_mul_f32_e32 v21, v149, v149
	v_fmac_f32_e32 v20, v150, v150
	v_fmac_f32_e32 v21, v148, v148
	v_add_f32_e32 v20, v20, v21
	v_mul_f32_e32 v21, v147, v147
	v_add_u32_e32 v15, 64, v15
	v_fmac_f32_e32 v21, v146, v146
	v_cmp_lt_i32_e32 vcc, v14, v15
	v_add_f32_e32 v20, v20, v21
	v_mul_f32_e32 v21, v145, v145
	v_cndmask_b32_e32 v14, v159, v14, vcc
	v_fmac_f32_e32 v21, v144, v144
	v_lshlrev_b32_e32 v14, 2, v14
	v_add_f32_e32 v21, v21, v20
	v_mov_b32_e32 v22, v21
	s_nop 1
	v_permlane16_swap_b32_e32 v22, v21
	v_xor_b32_e32 v20, 32, v159
	v_cmp_lt_i32_e32 vcc, v20, v15
	s_waitcnt lgkmcnt(0)
	v_add_f32_e32 v21, v21, v22
	v_cndmask_b32_e32 v15, v159, v20, vcc
	v_lshlrev_b32_e32 v20, 2, v15
	v_mov_b32_e32 v22, v21
	s_nop 1
	v_permlane32_swap_b32_e32 v22, v21
	v_add_u32_e32 v15, s64, v155
	s_and_saveexec_b64 s[46:47], s[0:1]
	v_readlane_b32 s96, v243, 61
	v_readlane_b32 s97, v243, 62
	s_cbranch_execz .LBB0_761
	s_waitcnt lgkmcnt(0)
	v_add_f32_e32 v21, v21, v22
	ds_write_b32 v15, v21
; #define LAS __attribute__((address_space(3)))
; #define EPI_BAR() do { asm volatile("s_waitcnt lgkmcnt(0)" ::: "memory"); __builtin_amdgcn_s_barrier(); asm volatile("" ::: "memory"); } while (0)
; __device__ __forceinline__ void head_ss(const f32x4 (&v)[2][2][4][2], float (&tot)[2][4][2], LAS float* X, int wr, int wc, int fr, int fq) {
; #pragma unroll
;     for (int ai = 0; ai < 2; ++ai)
; #pragma unroll
;         for (int m = 0; m < 4; ++m)
; #pragma unroll
;             for (int bj = 0; bj < 2; ++bj) {
;                 const f32x4 a = v[ai][bj][m][0], b = v[ai][bj][m][1];
;                 float s = (a[0] * a[0] + a[1] * a[1]) + (a[2] * a[2] + a[3] * a[3]) + (b[0] * b[0] + b[1] * b[1]) + (b[2] * b[2] + b[3] * b[3]);
;                 s += __shfl_xor(s, 16); s += __shfl_xor(s, 32);
;                 if (fq == 0) X[((ai * 128 + wr * 64 + m * 16 + fr) * 2 + bj) * 4 + wc] = s;
;             }
;     EPI_BAR();
.LBB0_761:
	s_or_b64 exec, exec, s[46:47]
	v_mul_f32_e32 v21, v127, v127
	s_waitcnt lgkmcnt(0)
	v_mul_f32_e32 v22, v125, v125
	v_fmac_f32_e32 v21, v126, v126
	v_fmac_f32_e32 v22, v124, v124
	v_add_f32_e32 v21, v21, v22
	v_mul_f32_e32 v22, v123, v123
	v_fmac_f32_e32 v22, v122, v122
	v_add_f32_e32 v21, v21, v22
	v_mul_f32_e32 v22, v121, v121
	v_fmac_f32_e32 v22, v120, v120
	v_add_f32_e32 v21, v22, v21
	v_mov_b32_e32 v22, v21
	s_nop 1
	v_permlane16_swap_b32_e32 v22, v21
	s_waitcnt lgkmcnt(0)
	v_add_f32_e32 v21, v21, v22
	v_mov_b32_e32 v22, v21
	s_nop 1
	v_permlane32_swap_b32_e32 v22, v21
	s_and_saveexec_b64 s[46:47], s[0:1]
	s_cbranch_execz .LBB0_763
	s_waitcnt lgkmcnt(0)
	v_add_f32_e32 v21, v21, v22
	ds_write_b32 v15, v21 offset:16
.LBB0_763:
	s_or_b64 exec, exec, s[46:47]
	v_mul_f32_e32 v21, v117, v117
	s_waitcnt lgkmcnt(0)
	v_mul_f32_e32 v22, v119, v119
	v_fmac_f32_e32 v21, v116, v116
	v_fmac_f32_e32 v22, v118, v118
	v_add_f32_e32 v21, v21, v22
	v_mul_f32_e32 v22, v113, v113
	v_fmac_f32_e32 v22, v112, v112
	v_add_f32_e32 v21, v21, v22
	v_mul_f32_e32 v22, v115, v115
	v_fmac_f32_e32 v22, v114, v114
	v_add_f32_e32 v21, v22, v21
	v_mov_b32_e32 v22, v21
	s_nop 1
	v_permlane16_swap_b32_e32 v22, v21
	s_waitcnt lgkmcnt(0)
	v_add_f32_e32 v21, v21, v22
	v_mov_b32_e32 v22, v21
	s_nop 1
	v_permlane32_swap_b32_e32 v22, v21
	s_and_saveexec_b64 s[46:47], s[0:1]
	s_cbranch_execz .LBB0_765
	s_waitcnt lgkmcnt(0)
	v_add_f32_e32 v21, v21, v22
	ds_write_b32 v15, v21 offset:512
.LBB0_765:
	s_or_b64 exec, exec, s[46:47]
	v_mul_f32_e32 v21, v111, v111
	s_waitcnt lgkmcnt(0)
	v_mul_f32_e32 v22, v109, v109
	v_fmac_f32_e32 v21, v110, v110
	v_fmac_f32_e32 v22, v108, v108
	v_add_f32_e32 v21, v21, v22
	v_mul_f32_e32 v22, v107, v107
	v_fmac_f32_e32 v22, v106, v106
	v_add_f32_e32 v21, v21, v22
	v_mul_f32_e32 v22, v105, v105
	v_fmac_f32_e32 v22, v104, v104
	v_add_f32_e32 v21, v22, v21
	v_mov_b32_e32 v22, v21
	s_nop 1
	v_permlane16_swap_b32_e32 v22, v21
	s_waitcnt lgkmcnt(0)
	v_add_f32_e32 v21, v21, v22
	v_mov_b32_e32 v22, v21
	s_nop 1
	v_permlane32_swap_b32_e32 v22, v21
	s_and_saveexec_b64 s[46:47], s[0:1]
	s_cbranch_execz .LBB0_767
	s_waitcnt lgkmcnt(0)
	v_add_f32_e32 v21, v21, v22
	ds_write_b32 v15, v21 offset:528
.LBB0_767:
	s_or_b64 exec, exec, s[46:47]
	v_mul_f32_e32 v21, v95, v95
	s_waitcnt lgkmcnt(0)
	v_mul_f32_e32 v22, v91, v91
	v_fmac_f32_e32 v21, v94, v94
	v_fmac_f32_e32 v22, v90, v90
	v_add_f32_e32 v21, v21, v22
	v_mul_f32_e32 v22, v93, v93
	v_fmac_f32_e32 v22, v92, v92
	v_add_f32_e32 v21, v21, v22
	v_mul_f32_e32 v22, v89, v89
	v_fmac_f32_e32 v22, v88, v88
	v_add_f32_e32 v21, v22, v21
	v_mov_b32_e32 v22, v21
	s_nop 1
	v_permlane16_swap_b32_e32 v22, v21
	s_waitcnt lgkmcnt(0)
	v_add_f32_e32 v21, v21, v22
	v_mov_b32_e32 v22, v21
	s_nop 1
	v_permlane32_swap_b32_e32 v22, v21
	s_and_saveexec_b64 s[46:47], s[0:1]
	s_cbranch_execz .LBB0_769
	s_waitcnt lgkmcnt(0)
	v_add_f32_e32 v21, v21, v22
	ds_write_b32 v15, v21 offset:1024
.LBB0_769:
	s_or_b64 exec, exec, s[46:47]
	v_mul_f32_e32 v21, v101, v101
	s_waitcnt lgkmcnt(0)
	v_mul_f32_e32 v22, v97, v97
	v_fmac_f32_e32 v21, v100, v100
	v_fmac_f32_e32 v22, v96, v96
	v_add_f32_e32 v21, v21, v22
	v_mul_f32_e32 v22, v99, v99
	v_fmac_f32_e32 v22, v98, v98
	v_add_f32_e32 v21, v21, v22
	v_mul_f32_e32 v22, v81, v81
	v_fmac_f32_e32 v22, v80, v80
	v_add_f32_e32 v21, v22, v21
	v_mov_b32_e32 v22, v21
	s_nop 1
	v_permlane16_swap_b32_e32 v22, v21
	s_waitcnt lgkmcnt(0)
	v_add_f32_e32 v21, v21, v22
	v_mov_b32_e32 v22, v21
	s_nop 1
	v_permlane32_swap_b32_e32 v22, v21
	s_and_saveexec_b64 s[46:47], s[0:1]
	s_cbranch_execz .LBB0_771
	s_waitcnt lgkmcnt(0)
	v_add_f32_e32 v21, v21, v22
	ds_write_b32 v15, v21 offset:1040
.LBB0_771:
	s_or_b64 exec, exec, s[46:47]
	v_mul_f32_e32 v21, v83, v83
	s_waitcnt lgkmcnt(0)
	v_mul_f32_e32 v22, v75, v75
	v_fmac_f32_e32 v21, v82, v82
	v_fmac_f32_e32 v22, v74, v74
	v_add_f32_e32 v21, v21, v22
	v_mul_f32_e32 v22, v77, v77
	v_fmac_f32_e32 v22, v76, v76
	v_add_f32_e32 v21, v21, v22
	v_mul_f32_e32 v22, v73, v73
	v_fmac_f32_e32 v22, v72, v72
	v_add_f32_e32 v21, v22, v21
	v_mov_b32_e32 v22, v21
	s_nop 1
	v_permlane16_swap_b32_e32 v22, v21
	s_waitcnt lgkmcnt(0)
	v_add_f32_e32 v21, v21, v22
	v_mov_b32_e32 v22, v21
	s_nop 1
	v_permlane32_swap_b32_e32 v22, v21
	s_and_saveexec_b64 s[46:47], s[0:1]
	s_cbranch_execz .LBB0_773
	s_waitcnt lgkmcnt(0)
	v_add_f32_e32 v21, v21, v22
	ds_write_b32 v15, v21 offset:1536
.LBB0_773:
	s_or_b64 exec, exec, s[46:47]
	v_mul_f32_e32 v21, v69, v69
	s_waitcnt lgkmcnt(0)
	v_mul_f32_e32 v22, v71, v71
	v_fmac_f32_e32 v21, v68, v68
	v_fmac_f32_e32 v22, v70, v70
	v_add_f32_e32 v21, v21, v22
	v_mul_f32_e32 v22, v65, v65
	v_fmac_f32_e32 v22, v64, v64
	v_add_f32_e32 v21, v21, v22
	v_mul_f32_e32 v22, v67, v67
	v_fmac_f32_e32 v22, v66, v66
	v_add_f32_e32 v21, v22, v21
	v_mov_b32_e32 v22, v21
	s_nop 1
	v_permlane16_swap_b32_e32 v22, v21
	s_waitcnt lgkmcnt(0)
	v_add_f32_e32 v21, v21, v22
	v_mov_b32_e32 v22, v21
	s_nop 1
	v_permlane32_swap_b32_e32 v22, v21
	s_and_saveexec_b64 s[46:47], s[0:1]
	s_cbranch_execz .LBB0_775
	s_waitcnt lgkmcnt(0)
	v_add_f32_e32 v21, v21, v22
	ds_write_b32 v15, v21 offset:1552
; #define LAS __attribute__((address_space(3)))
; #define EPI_BAR() do { asm volatile("s_waitcnt lgkmcnt(0)" ::: "memory"); __builtin_amdgcn_s_barrier(); asm volatile("" ::: "memory"); } while (0)
; __device__ __forceinline__ void head_ss(const f32x4 (&v)[2][2][4][2], float (&tot)[2][4][2], LAS float* X, int wr, int wc, int fr, int fq) {
; #pragma unroll
;     for (int ai = 0; ai < 2; ++ai)
; #pragma unroll
;         for (int m = 0; m < 4; ++m)
; #pragma unroll
;             for (int bj = 0; bj < 2; ++bj) {
;                 const f32x4 a = v[ai][bj][m][0], b = v[ai][bj][m][1];
;                 float s = (a[0] * a[0] + a[1] * a[1]) + (a[2] * a[2] + a[3] * a[3]) + (b[0] * b[0] + b[1] * b[1]) + (b[2] * b[2] + b[3] * b[3]);
;                 s += __shfl_xor(s, 16); s += __shfl_xor(s, 32);
;                 if (fq == 0) X[((ai * 128 + wr * 64 + m * 16 + fr) * 2 + bj) * 4 + wc] = s;
;             }
;     EPI_BAR();
.LBB0_775:
	s_or_b64 exec, exec, s[46:47]
	v_mul_f32_e32 v21, v103, v103
	s_waitcnt lgkmcnt(0)
	v_mul_f32_e32 v22, v87, v87
	v_fmac_f32_e32 v21, v102, v102
	v_fmac_f32_e32 v22, v86, v86
	v_add_f32_e32 v21, v21, v22
	v_mul_f32_e32 v22, v85, v85
	v_fmac_f32_e32 v22, v84, v84
	v_add_f32_e32 v21, v21, v22
	v_mul_f32_e32 v22, v79, v79
	v_fmac_f32_e32 v22, v78, v78
	v_add_f32_e32 v21, v22, v21
	v_mov_b32_e32 v22, v21
	s_nop 1
	v_permlane16_swap_b32_e32 v22, v21
	s_waitcnt lgkmcnt(0)
	v_add_f32_e32 v21, v21, v22
	v_mov_b32_e32 v22, v21
	s_nop 1
	v_permlane32_swap_b32_e32 v22, v21
	s_and_saveexec_b64 s[46:47], s[0:1]
	s_cbranch_execz .LBB0_777
	s_waitcnt lgkmcnt(0)
	v_add_f32_e32 v21, v21, v22
	ds_write_b32 v15, v21 offset:4096
.LBB0_777:
	s_or_b64 exec, exec, s[46:47]
	v_mul_f32_e32 v21, v63, v63
	s_waitcnt lgkmcnt(0)
	v_mul_f32_e32 v22, v55, v55
	v_fmac_f32_e32 v21, v62, v62
	v_fmac_f32_e32 v22, v54, v54
	v_add_f32_e32 v21, v21, v22
	v_mul_f32_e32 v22, v59, v59
	v_fmac_f32_e32 v22, v58, v58
	v_add_f32_e32 v21, v21, v22
	v_mul_f32_e32 v22, v53, v53
	v_fmac_f32_e32 v22, v52, v52
	v_add_f32_e32 v21, v22, v21
	v_mov_b32_e32 v22, v21
	s_nop 1
	v_permlane16_swap_b32_e32 v22, v21
	s_waitcnt lgkmcnt(0)
	v_add_f32_e32 v21, v21, v22
	v_mov_b32_e32 v22, v21
	s_nop 1
	v_permlane32_swap_b32_e32 v22, v21
	s_and_saveexec_b64 s[46:47], s[0:1]
	s_cbranch_execz .LBB0_779
	s_waitcnt lgkmcnt(0)
	v_add_f32_e32 v21, v21, v22
	ds_write_b32 v15, v21 offset:4112
.LBB0_779:
	s_or_b64 exec, exec, s[46:47]
	v_mul_f32_e32 v21, v61, v61
	s_waitcnt lgkmcnt(0)
	v_mul_f32_e32 v22, v51, v51
	v_fmac_f32_e32 v21, v60, v60
	v_fmac_f32_e32 v22, v50, v50
	v_add_f32_e32 v21, v21, v22
	v_mul_f32_e32 v22, v57, v57
	v_fmac_f32_e32 v22, v56, v56
	v_add_f32_e32 v21, v21, v22
	v_mul_f32_e32 v22, v47, v47
	v_fmac_f32_e32 v22, v46, v46
	v_add_f32_e32 v21, v22, v21
	v_mov_b32_e32 v22, v21
	s_nop 1
	v_permlane16_swap_b32_e32 v22, v21
	s_waitcnt lgkmcnt(0)
	v_add_f32_e32 v21, v21, v22
	v_mov_b32_e32 v22, v21
	s_nop 1
	v_permlane32_swap_b32_e32 v22, v21
	s_and_saveexec_b64 s[46:47], s[0:1]
	s_cbranch_execz .LBB0_781
	s_waitcnt lgkmcnt(0)
	v_add_f32_e32 v21, v21, v22
	ds_write_b32 v15, v21 offset:4608
.LBB0_781:
	s_or_b64 exec, exec, s[46:47]
	v_mul_f32_e32 v21, v49, v49
	s_waitcnt lgkmcnt(0)
	v_mul_f32_e32 v22, v43, v43
	v_fmac_f32_e32 v21, v48, v48
	v_fmac_f32_e32 v22, v42, v42
	v_add_f32_e32 v21, v21, v22
	v_mul_f32_e32 v22, v45, v45
	v_fmac_f32_e32 v22, v44, v44
	v_add_f32_e32 v21, v21, v22
	v_mul_f32_e32 v22, v41, v41
	v_fmac_f32_e32 v22, v40, v40
	v_add_f32_e32 v21, v22, v21
	v_mov_b32_e32 v22, v21
	s_nop 1
	v_permlane16_swap_b32_e32 v22, v21
	s_waitcnt lgkmcnt(0)
	v_add_f32_e32 v21, v21, v22
	v_mov_b32_e32 v22, v21
	s_nop 1
	v_permlane32_swap_b32_e32 v22, v21
	s_and_saveexec_b64 s[46:47], s[0:1]
	s_cbranch_execz .LBB0_783
	s_waitcnt lgkmcnt(0)
	v_add_f32_e32 v21, v21, v22
	ds_write_b32 v15, v21 offset:4624
.LBB0_783:
	s_or_b64 exec, exec, s[46:47]
	v_mul_f32_e32 v21, v37, v37
	s_waitcnt lgkmcnt(0)
	v_mul_f32_e32 v22, v33, v33
	v_fmac_f32_e32 v21, v36, v36
	v_fmac_f32_e32 v22, v32, v32
	v_add_f32_e32 v21, v21, v22
	v_mul_f32_e32 v22, v35, v35
	v_fmac_f32_e32 v22, v34, v34
	v_add_f32_e32 v21, v21, v22
	v_mul_f32_e32 v22, v31, v31
	v_fmac_f32_e32 v22, v30, v30
	v_add_f32_e32 v21, v22, v21
	v_mov_b32_e32 v22, v21
	s_nop 1
	v_permlane16_swap_b32_e32 v22, v21
	s_waitcnt lgkmcnt(0)
	v_add_f32_e32 v21, v21, v22
	v_mov_b32_e32 v22, v21
	s_nop 1
	v_permlane32_swap_b32_e32 v22, v21
	s_and_saveexec_b64 s[46:47], s[0:1]
	s_cbranch_execz .LBB0_785
	s_waitcnt lgkmcnt(0)
	v_add_f32_e32 v21, v21, v22
	ds_write_b32 v15, v21 offset:5120
.LBB0_785:
	s_or_b64 exec, exec, s[46:47]
	v_mul_f32_e32 v21, v29, v29
	s_waitcnt lgkmcnt(0)
	v_mul_f32_e32 v22, v25, v25
	v_fmac_f32_e32 v21, v28, v28
	v_fmac_f32_e32 v22, v24, v24
	v_add_f32_e32 v21, v21, v22
	v_mul_f32_e32 v22, v27, v27
	v_fmac_f32_e32 v22, v26, v26
	v_mul_f32_e32 v17, v17, v17
	v_add_f32_e32 v21, v21, v22
	v_fmac_f32_e32 v17, v16, v16
	v_add_f32_e32 v16, v17, v21
	v_mov_b32_e32 v17, v16
	s_nop 1
	v_permlane16_swap_b32_e32 v17, v16
	s_waitcnt lgkmcnt(0)
	v_add_f32_e32 v16, v16, v17
	v_mov_b32_e32 v17, v16
	s_nop 1
	v_permlane32_swap_b32_e32 v17, v16
	s_and_saveexec_b64 s[46:47], s[0:1]
	s_cbranch_execz .LBB0_787
	s_waitcnt lgkmcnt(0)
	v_add_f32_e32 v16, v16, v17
	ds_write_b32 v15, v16 offset:5136
.LBB0_787:
	s_or_b64 exec, exec, s[46:47]
	v_mul_f32_e32 v16, v19, v19
	v_mul_f32_e32 v11, v11, v11
	v_fmac_f32_e32 v16, v18, v18
	v_fmac_f32_e32 v11, v10, v10
	v_add_f32_e32 v10, v16, v11
	v_mul_f32_e32 v11, v13, v13
	v_fmac_f32_e32 v11, v12, v12
	v_mul_f32_e32 v9, v9, v9
	v_add_f32_e32 v10, v10, v11
	v_fmac_f32_e32 v9, v8, v8
	v_add_f32_e32 v8, v9, v10
	v_mov_b32_e32 v9, v8
	s_nop 1
	v_permlane16_swap_b32_e32 v9, v8
	s_waitcnt lgkmcnt(0)
	v_add_f32_e32 v8, v8, v9
	v_mov_b32_e32 v9, v8
	s_nop 1
	v_permlane32_swap_b32_e32 v9, v8
	s_and_saveexec_b64 s[46:47], s[0:1]
	s_cbranch_execz .LBB0_789
	s_waitcnt lgkmcnt(0)
	v_add_f32_e32 v8, v8, v9
	ds_write_b32 v15, v8 offset:5632
.LBB0_789:
	s_or_b64 exec, exec, s[46:47]
	v_mul_f32_e32 v5, v5, v5
	v_fmac_f32_e32 v5, v4, v4
	v_mul_f32_e32 v4, v7, v7
	v_fmac_f32_e32 v4, v6, v6
	v_mul_f32_e32 v1, v1, v1
	v_add_f32_e32 v4, v5, v4
	v_fmac_f32_e32 v1, v0, v0
	v_add_f32_e32 v0, v4, v1
	v_mul_f32_e32 v1, v3, v3
	v_fmac_f32_e32 v1, v2, v2
	v_add_f32_e32 v0, v1, v0
	v_mov_b32_e32 v1, v0
	s_nop 1
	v_permlane16_swap_b32_e32 v1, v0
	s_waitcnt lgkmcnt(0)
	v_add_f32_e32 v0, v0, v1
	v_mov_b32_e32 v1, v0
	s_nop 1
	v_permlane32_swap_b32_e32 v1, v0
	s_and_saveexec_b64 s[46:47], s[0:1]
	s_cbranch_execz .LBB0_791
	s_waitcnt lgkmcnt(0)
	v_add_f32_e32 v0, v0, v1
	ds_write_b32 v15, v0 offset:5648

; #define LAS __attribute__((address_space(3)))
; #define EPI_BAR() do { asm volatile("s_waitcnt lgkmcnt(0)" ::: "memory"); __builtin_amdgcn_s_barrier(); asm volatile("" ::: "memory"); } while (0)
; #define FOR_AI_M _Pragma("unroll") for (int ai = 0; ai < 2; ++ai) _Pragma("unroll") for (int m = 0; m < 4; ++m)
; #define FOR_BJ _Pragma("unroll") for (int bj = 0; bj < 2; ++bj)
; __device__ __forceinline__ void head_ss(const f32x4 (&v)[2][2][4][2], float (&tot)[2][4][2], LAS float* X, int wr, int wc, int fr, int fq) {
; #pragma unroll
;     for (int ai = 0; ai < 2; ++ai)
; #pragma unroll
;         for (int m = 0; m < 4; ++m)
; #pragma unroll
;             for (int bj = 0; bj < 2; ++bj) {
;                 const f32x4 a = v[ai][bj][m][0], b = v[ai][bj][m][1];
;                 float s = (a[0] * a[0] + a[1] * a[1]) + (a[2] * a[2] + a[3] * a[3]) + (b[0] * b[0] + b[1] * b[1]) + (b[2] * b[2] + b[3] * b[3]);
;                 s += __shfl_xor(s, 16); s += __shfl_xor(s, 32);
;                 if (fq == 0) X[((ai * 128 + wr * 64 + m * 16 + fr) * 2 + bj) * 4 + wc] = s;
;             }
;     EPI_BAR();
;     __device__ __forceinline__ void operator()(f32x4 (&acc)[2][2][4][2], const Unit& u, int wr, int wc, int fr, int fq) const {
;         FOR_AI_M { const int grow = u.pm * BM + ai * HALF + wr * 64 + m * 16 + fr;
;             const f32x4 a0 = *(const f32x4*)(SS2 + (size_t)grow * 8), a1 = *(const f32x4*)(SS2 + (size_t)grow * 8 + 4);
;             const float r2 = rsqrtf(((a0[0] + a0[1]) + (a0[2] + a0[3]) + (a1[0] + a1[1]) + (a1[2] + a1[3])) * (1.f / 2048.f) + EPS);
;             FOR_BJ { acc[ai][bj][m][0] *= r2; acc[ai][bj][m][1] *= r2; } }
;         float tot[2][4][2]; head_ss(acc, tot, X, wr, wc, fr, fq);
.LBB0_867:
	v_lshl_add_u32 v210, s4, 8, v179
	v_ashrrev_i32_e32 v211, 31, v210
	v_lshlrev_b64 v[128:129], 5, v[210:211]
	v_or_b32_e32 v208, 16, v210
	s_waitcnt vmcnt(0)
	v_lshl_add_u64 v[128:129], s[6:7], 0, v[128:129]
	v_ashrrev_i32_e32 v209, 31, v208
	global_load_dwordx4 v[212:215], v[128:129], off
	global_load_dwordx4 v[222:225], v[128:129], off offset:16
	v_lshlrev_b64 v[128:129], 5, v[208:209]
	v_lshl_add_u64 v[128:129], s[6:7], 0, v[128:129]
	global_load_dwordx4 v[226:229], v[128:129], off
	global_load_dwordx4 v[230:233], v[128:129], off offset:16
	v_or_b32_e32 v206, 32, v210
	v_or_b32_e32 v204, 48, v210
	v_add_u32_e32 v202, 0x80, v210
	v_add_u32_e32 v200, 0x90, v210
	v_add_u32_e32 v198, 0xa0, v210
	v_add_u32_e32 v196, 0xb0, v210
	v_ashrrev_i32_e32 v207, 31, v206
	v_ashrrev_i32_e32 v205, 31, v204
	v_ashrrev_i32_e32 v203, 31, v202
	v_ashrrev_i32_e32 v201, 31, v200
	v_ashrrev_i32_e32 v199, 31, v198
	v_ashrrev_i32_e32 v197, 31, v196
	v_lshlrev_b64 v[128:129], 5, v[206:207]
	v_lshlrev_b64 v[130:131], 5, v[204:205]
	v_lshlrev_b64 v[132:133], 5, v[202:203]
	v_lshlrev_b64 v[134:135], 5, v[200:201]
	v_lshlrev_b64 v[136:137], 5, v[198:199]
	v_lshlrev_b64 v[138:139], 5, v[196:197]
	v_lshl_add_u64 v[128:129], s[6:7], 0, v[128:129]
	v_lshl_add_u64 v[130:131], s[6:7], 0, v[130:131]
	v_lshl_add_u64 v[132:133], s[6:7], 0, v[132:133]
	v_lshl_add_u64 v[134:135], s[6:7], 0, v[134:135]
	v_lshl_add_u64 v[140:141], s[6:7], 0, v[136:137]
	v_lshl_add_u64 v[234:235], s[6:7], 0, v[138:139]
	global_load_dwordx4 v[168:171], v[128:129], off offset:16
	global_load_dwordx4 v[172:175], v[128:129], off
	global_load_dwordx4 v[160:163], v[130:131], off offset:16
	global_load_dwordx4 v[164:167], v[130:131], off
	global_load_dwordx4 v[152:155], v[132:133], off offset:16
	global_load_dwordx4 v[156:159], v[132:133], off
	global_load_dwordx4 v[144:147], v[134:135], off offset:16
	global_load_dwordx4 v[148:151], v[134:135], off
	global_load_dwordx4 v[136:139], v[140:141], off offset:16
	s_nop 0
	global_load_dwordx4 v[140:143], v[140:141], off
	s_nop 0
	global_load_dwordx4 v[128:131], v[234:235], off offset:16
	global_load_dwordx4 v[132:135], v[234:235], off
	v_and_b32_e32 v234, 64, v221
	v_add_u32_e32 v237, 64, v234
	v_xor_b32_e32 v236, 16, v221
	v_cmp_lt_i32_e64 s[4:5], v236, v237
	s_waitcnt vmcnt(0)
	v_mov_b32_e32 v234, v213
	v_mov_b32_e32 v235, v214
	v_mov_b32_e32 v213, v215
	v_mov_b32_e32 v214, v224
	v_mov_b32_e32 v215, v222
	v_mov_b32_e32 v222, v225
	v_pk_add_f32 v[214:215], v[214:215], v[222:223]
	v_mov_b32_e32 v222, v227
	v_mov_b32_e32 v223, v228
	v_mov_b32_e32 v227, v229
	v_pk_add_f32 v[212:213], v[234:235], v[212:213]
	v_mov_b32_e32 v224, v232
	v_mov_b32_e32 v225, v230
	v_mov_b32_e32 v230, v233
	v_pk_add_f32 v[222:223], v[222:223], v[226:227]
	v_pk_add_f32 v[224:225], v[224:225], v[230:231]
	v_mov_b32_e32 v227, v212
	v_mov_b32_e32 v226, v222
	v_mov_b32_e32 v212, v223
	v_mov_b32_e32 v229, v215
	v_mov_b32_e32 v228, v225
	v_pk_add_f32 v[212:213], v[226:227], v[212:213]
	v_mov_b32_e32 v225, v214
	v_pk_add_f32 v[212:213], v[212:213], v[228:229]
	s_nop 0
	v_pk_add_f32 v[212:213], v[224:225], v[212:213]
	s_nop 0
	v_pk_fma_f32 v[212:213], v[212:213], s[20:21], v[194:195] op_sel_hi:[1,0,0]
	s_nop 0
	v_mul_f32_e32 v214, 0x4b800000, v213
	v_cmp_gt_f32_e32 vcc, s67, v213
	s_nop 1
	v_cndmask_b32_e32 v213, v213, v214, vcc
	v_rsq_f32_e32 v213, v213
	v_cndmask_b32_e64 v214, v221, v236, s[4:5]
	v_lshlrev_b32_e32 v222, 2, v214
	v_mul_f32_e32 v214, 0x45800000, v213
	v_cndmask_b32_e32 v214, v213, v214, vcc
	v_pk_mul_f32 v[126:127], v[126:127], v[214:215] op_sel_hi:[1,0]
	v_pk_mul_f32 v[124:125], v[124:125], v[214:215] op_sel_hi:[1,0]
	v_pk_mul_f32 v[122:123], v[122:123], v[214:215] op_sel_hi:[1,0]
	v_pk_mul_f32 v[120:121], v[120:121], v[214:215] op_sel_hi:[1,0]
	v_mul_f32_e32 v213, v125, v125
	v_mul_f32_e32 v215, v127, v127
	v_mul_f32_e32 v223, v121, v121
	v_fmac_f32_e32 v213, v124, v124
	v_fmac_f32_e32 v215, v126, v126
	v_mul_f32_e32 v224, v123, v123
	v_fmac_f32_e32 v223, v120, v120
	v_add_f32_e32 v213, v213, v215
	v_add_f32_e32 v213, v223, v213
	v_fmac_f32_e32 v224, v122, v122
	v_add_f32_e32 v213, v224, v213
	v_mov_b32_e32 v215, v213
	s_nop 1
	v_permlane16_swap_b32_e32 v215, v213
	v_xor_b32_e32 v223, 32, v221
	v_cmp_lt_i32_e32 vcc, v223, v237
	s_waitcnt lgkmcnt(0)
	v_add_f32_e32 v213, v213, v215
	v_cndmask_b32_e32 v223, v221, v223, vcc
	v_lshlrev_b32_e32 v224, 2, v223
	v_mov_b32_e32 v215, v213
	s_nop 1
	v_permlane32_swap_b32_e32 v215, v213
	v_cmp_gt_f32_e32 vcc, s67, v212
	v_add_u32_e32 v223, s79, v216
	s_and_saveexec_b64 s[4:5], s[0:1]
	s_cbranch_execz .LBB0_869
	s_waitcnt lgkmcnt(0)
	v_add_f32_e32 v213, v213, v215
	ds_write_b32 v223, v213
.LBB0_869:
	s_or_b64 exec, exec, s[4:5]
	s_waitcnt lgkmcnt(0)
	v_mov_b32_e32 v215, v214
	v_mov_b32_e32 v226, v214
	v_mov_b32_e32 v227, v214
	v_pk_mul_f32 v[118:119], v[118:119], v[226:227]
	v_pk_mul_f32 v[116:117], v[116:117], v[214:215]
	v_pk_mul_f32 v[112:113], v[112:113], v[214:215]
	v_mul_f32_e32 v213, v117, v117
	v_mul_f32_e32 v214, v119, v119
	v_fmac_f32_e32 v213, v116, v116
	v_fmac_f32_e32 v214, v118, v118
	v_add_f32_e32 v213, v213, v214
	v_mul_f32_e32 v214, v113, v113
	v_pk_mul_f32 v[114:115], v[114:115], v[226:227]
	v_fmac_f32_e32 v214, v112, v112
	v_add_f32_e32 v213, v214, v213
	v_mul_f32_e32 v214, v115, v115
	v_fmac_f32_e32 v214, v114, v114
	v_add_f32_e32 v213, v214, v213
	v_mov_b32_e32 v214, v213
	s_nop 1
	v_permlane16_swap_b32_e32 v214, v213
	s_waitcnt lgkmcnt(0)
	v_add_f32_e32 v213, v213, v214
	v_mov_b32_e32 v214, v213
	s_nop 1
	v_permlane32_swap_b32_e32 v214, v213
	s_and_saveexec_b64 s[4:5], s[0:1]
	s_cbranch_execz .LBB0_871
	s_waitcnt lgkmcnt(0)
	v_add_f32_e32 v213, v213, v214
	ds_write_b32 v223, v213 offset:16
; #define LAS __attribute__((address_space(3)))
; #define EPI_BAR() do { asm volatile("s_waitcnt lgkmcnt(0)" ::: "memory"); __builtin_amdgcn_s_barrier(); asm volatile("" ::: "memory"); } while (0)
; #define FOR_AI_M _Pragma("unroll") for (int ai = 0; ai < 2; ++ai) _Pragma("unroll") for (int m = 0; m < 4; ++m)
; #define FOR_BJ _Pragma("unroll") for (int bj = 0; bj < 2; ++bj)
; __device__ __forceinline__ void head_ss(const f32x4 (&v)[2][2][4][2], float (&tot)[2][4][2], LAS float* X, int wr, int wc, int fr, int fq) {
; #pragma unroll
;     for (int ai = 0; ai < 2; ++ai)
; #pragma unroll
;         for (int m = 0; m < 4; ++m)
; #pragma unroll
;             for (int bj = 0; bj < 2; ++bj) {
;                 const f32x4 a = v[ai][bj][m][0], b = v[ai][bj][m][1];
;                 float s = (a[0] * a[0] + a[1] * a[1]) + (a[2] * a[2] + a[3] * a[3]) + (b[0] * b[0] + b[1] * b[1]) + (b[2] * b[2] + b[3] * b[3]);
;                 s += __shfl_xor(s, 16); s += __shfl_xor(s, 32);
;                 if (fq == 0) X[((ai * 128 + wr * 64 + m * 16 + fr) * 2 + bj) * 4 + wc] = s;
;             }
;     EPI_BAR();
;     __device__ __forceinline__ void operator()(f32x4 (&acc)[2][2][4][2], const Unit& u, int wr, int wc, int fr, int fq) const {
;         FOR_AI_M { const int grow = u.pm * BM + ai * HALF + wr * 64 + m * 16 + fr;
;             const f32x4 a0 = *(const f32x4*)(SS2 + (size_t)grow * 8), a1 = *(const f32x4*)(SS2 + (size_t)grow * 8 + 4);
;             const float r2 = rsqrtf(((a0[0] + a0[1]) + (a0[2] + a0[3]) + (a1[0] + a1[1]) + (a1[2] + a1[3])) * (1.f / 2048.f) + EPS);
;             FOR_BJ { acc[ai][bj][m][0] *= r2; acc[ai][bj][m][1] *= r2; } }
;         float tot[2][4][2]; head_ss(acc, tot, X, wr, wc, fr, fq);
.LBB0_871:
	s_or_b64 exec, exec, s[4:5]
	v_mul_f32_e32 v213, 0x4b800000, v212
	v_cndmask_b32_e32 v212, v212, v213, vcc
	v_rsq_f32_e32 v212, v212
	s_nop 0
	v_mul_f32_e32 v213, 0x45800000, v212
	v_cndmask_b32_e32 v212, v212, v213, vcc
	v_pk_mul_f32 v[110:111], v[110:111], v[212:213] op_sel_hi:[1,0]
	v_pk_mul_f32 v[108:109], v[108:109], v[212:213] op_sel_hi:[1,0]
	v_pk_mul_f32 v[106:107], v[106:107], v[212:213] op_sel_hi:[1,0]
	v_pk_mul_f32 v[104:105], v[104:105], v[212:213] op_sel_hi:[1,0]
	v_mul_f32_e32 v213, v109, v109
	s_waitcnt lgkmcnt(0)
	v_mul_f32_e32 v214, v111, v111
	v_fmac_f32_e32 v213, v108, v108
	v_fmac_f32_e32 v214, v110, v110
	v_add_f32_e32 v213, v213, v214
	v_mul_f32_e32 v214, v105, v105
	v_fmac_f32_e32 v214, v104, v104
	v_add_f32_e32 v213, v214, v213
	v_mul_f32_e32 v214, v107, v107
	v_fmac_f32_e32 v214, v106, v106
	v_add_f32_e32 v213, v214, v213
	v_mov_b32_e32 v214, v213
	s_nop 1
	v_permlane16_swap_b32_e32 v214, v213
	s_waitcnt lgkmcnt(0)
	v_add_f32_e32 v213, v213, v214
	v_mov_b32_e32 v214, v213
	s_nop 1
	v_permlane32_swap_b32_e32 v214, v213
	s_and_saveexec_b64 s[4:5], s[0:1]
	s_cbranch_execz .LBB0_873
	s_waitcnt lgkmcnt(0)
	v_add_f32_e32 v213, v213, v214
	ds_write_b32 v223, v213 offset:512
.LBB0_873:
	s_or_b64 exec, exec, s[4:5]
	v_mov_b32_e32 v213, v212
	s_waitcnt lgkmcnt(0)
	v_mov_b32_e32 v214, v212
	v_mov_b32_e32 v215, v212
	v_pk_mul_f32 v[102:103], v[102:103], v[214:215]
	v_pk_mul_f32 v[100:101], v[100:101], v[212:213]
	v_pk_mul_f32 v[96:97], v[96:97], v[212:213]
	v_mul_f32_e32 v212, v101, v101
	v_mul_f32_e32 v213, v103, v103
	v_fmac_f32_e32 v212, v100, v100
	v_fmac_f32_e32 v213, v102, v102
	v_add_f32_e32 v212, v212, v213
	v_mul_f32_e32 v213, v97, v97
	v_pk_mul_f32 v[98:99], v[98:99], v[214:215]
	v_fmac_f32_e32 v213, v96, v96
	v_add_f32_e32 v212, v213, v212
	v_mul_f32_e32 v213, v99, v99
	v_fmac_f32_e32 v213, v98, v98
	v_add_f32_e32 v212, v213, v212
	v_mov_b32_e32 v213, v212
	s_nop 1
	v_permlane16_swap_b32_e32 v213, v212
	s_waitcnt lgkmcnt(0)
	v_add_f32_e32 v212, v212, v213
	v_mov_b32_e32 v213, v212
	s_nop 1
	v_permlane32_swap_b32_e32 v213, v212
	s_and_saveexec_b64 s[4:5], s[0:1]
	s_cbranch_execz .LBB0_875
	s_waitcnt lgkmcnt(0)
	v_add_f32_e32 v212, v212, v213
	ds_write_b32 v223, v212 offset:528
.LBB0_875:
	s_or_b64 exec, exec, s[4:5]
	v_mov_b32_e32 v212, v173
	s_waitcnt lgkmcnt(0)
	v_mov_b32_e32 v213, v174
	v_mov_b32_e32 v173, v175
	v_mov_b32_e32 v174, v170
	v_mov_b32_e32 v175, v168
	v_mov_b32_e32 v168, v171
	v_mov_b32_e32 v170, v165
	v_mov_b32_e32 v171, v166
	v_mov_b32_e32 v165, v167
	v_pk_add_f32 v[172:173], v[212:213], v[172:173]
	v_pk_add_f32 v[164:165], v[170:171], v[164:165]
	v_mov_b32_e32 v166, v162
	v_mov_b32_e32 v167, v160
	v_mov_b32_e32 v160, v163
	v_pk_add_f32 v[168:169], v[174:175], v[168:169]
	v_pk_add_f32 v[160:161], v[166:167], v[160:161]
	v_mov_b32_e32 v162, v164
	v_mov_b32_e32 v163, v172
	v_mov_b32_e32 v172, v165
	v_pk_add_f32 v[162:163], v[162:163], v[172:173]
	v_mov_b32_e32 v164, v161
	v_mov_b32_e32 v165, v169
	v_pk_add_f32 v[162:163], v[162:163], v[164:165]
	v_mov_b32_e32 v161, v168
	v_pk_add_f32 v[160:161], v[160:161], v[162:163]
	s_nop 0
	v_pk_fma_f32 v[160:161], v[160:161], s[20:21], v[194:195] op_sel_hi:[1,0,0]
	s_nop 0
	v_mul_f32_e32 v162, 0x4b800000, v161
	v_cmp_gt_f32_e32 vcc, s67, v161
	s_nop 1
	v_cndmask_b32_e32 v161, v161, v162, vcc
	v_rsq_f32_e32 v161, v161
	s_nop 0
	v_mul_f32_e32 v162, 0x45800000, v161
	v_cndmask_b32_e32 v162, v161, v162, vcc
	v_pk_mul_f32 v[94:95], v[94:95], v[162:163] op_sel_hi:[1,0]
	v_pk_mul_f32 v[92:93], v[92:93], v[162:163] op_sel_hi:[1,0]
	v_pk_mul_f32 v[90:91], v[90:91], v[162:163] op_sel_hi:[1,0]
	v_pk_mul_f32 v[88:89], v[88:89], v[162:163] op_sel_hi:[1,0]
	v_mul_f32_e32 v161, v93, v93
	v_mul_f32_e32 v163, v95, v95
	v_fmac_f32_e32 v161, v92, v92
	v_fmac_f32_e32 v163, v94, v94
	v_add_f32_e32 v161, v161, v163
	v_mul_f32_e32 v163, v89, v89
	v_fmac_f32_e32 v163, v88, v88
	v_add_f32_e32 v161, v163, v161
	v_mul_f32_e32 v163, v91, v91
	v_fmac_f32_e32 v163, v90, v90
	v_add_f32_e32 v161, v163, v161
	v_mov_b32_e32 v163, v161
	s_nop 1
	v_permlane16_swap_b32_e32 v163, v161
	v_cmp_gt_f32_e32 vcc, s67, v160
	s_waitcnt lgkmcnt(0)
	v_add_f32_e32 v161, v161, v163
	v_mov_b32_e32 v163, v161
	s_nop 1
	v_permlane32_swap_b32_e32 v163, v161
	s_and_saveexec_b64 s[4:5], s[0:1]
	s_cbranch_execz .LBB0_877
	s_waitcnt lgkmcnt(0)
	v_add_f32_e32 v161, v161, v163
	ds_write_b32 v223, v161 offset:1024
.LBB0_877:
	s_or_b64 exec, exec, s[4:5]
	s_waitcnt lgkmcnt(0)
	v_mov_b32_e32 v163, v162
	v_mov_b32_e32 v164, v162
	v_mov_b32_e32 v165, v162
	v_pk_mul_f32 v[86:87], v[86:87], v[164:165]
	v_pk_mul_f32 v[84:85], v[84:85], v[162:163]
	v_pk_mul_f32 v[80:81], v[80:81], v[162:163]
	v_mul_f32_e32 v161, v85, v85
	v_mul_f32_e32 v162, v87, v87
	v_fmac_f32_e32 v161, v84, v84
	v_fmac_f32_e32 v162, v86, v86
	v_add_f32_e32 v161, v161, v162
	v_mul_f32_e32 v162, v81, v81
	v_pk_mul_f32 v[82:83], v[82:83], v[164:165]
	v_fmac_f32_e32 v162, v80, v80
	v_add_f32_e32 v161, v162, v161
	v_mul_f32_e32 v162, v83, v83
	v_fmac_f32_e32 v162, v82, v82
	v_add_f32_e32 v161, v162, v161
	v_mov_b32_e32 v162, v161
	s_nop 1
	v_permlane16_swap_b32_e32 v162, v161
	s_waitcnt lgkmcnt(0)
	v_add_f32_e32 v161, v161, v162
	v_mov_b32_e32 v162, v161
	s_nop 1
	v_permlane32_swap_b32_e32 v162, v161
	s_and_saveexec_b64 s[4:5], s[0:1]
	s_cbranch_execz .LBB0_879
	s_waitcnt lgkmcnt(0)
	v_add_f32_e32 v161, v161, v162
	ds_write_b32 v223, v161 offset:1040
; #define LAS __attribute__((address_space(3)))
; #define EPI_BAR() do { asm volatile("s_waitcnt lgkmcnt(0)" ::: "memory"); __builtin_amdgcn_s_barrier(); asm volatile("" ::: "memory"); } while (0)
; #define FOR_AI_M _Pragma("unroll") for (int ai = 0; ai < 2; ++ai) _Pragma("unroll") for (int m = 0; m < 4; ++m)
; #define FOR_BJ _Pragma("unroll") for (int bj = 0; bj < 2; ++bj)
; __device__ __forceinline__ void head_ss(const f32x4 (&v)[2][2][4][2], float (&tot)[2][4][2], LAS float* X, int wr, int wc, int fr, int fq) {
; #pragma unroll
;     for (int ai = 0; ai < 2; ++ai)
; #pragma unroll
;         for (int m = 0; m < 4; ++m)
; #pragma unroll
;             for (int bj = 0; bj < 2; ++bj) {
;                 const f32x4 a = v[ai][bj][m][0], b = v[ai][bj][m][1];
;                 float s = (a[0] * a[0] + a[1] * a[1]) + (a[2] * a[2] + a[3] * a[3]) + (b[0] * b[0] + b[1] * b[1]) + (b[2] * b[2] + b[3] * b[3]);
;                 s += __shfl_xor(s, 16); s += __shfl_xor(s, 32);
;                 if (fq == 0) X[((ai * 128 + wr * 64 + m * 16 + fr) * 2 + bj) * 4 + wc] = s;
;             }
;     EPI_BAR();
;     __device__ __forceinline__ void operator()(f32x4 (&acc)[2][2][4][2], const Unit& u, int wr, int wc, int fr, int fq) const {
;         FOR_AI_M { const int grow = u.pm * BM + ai * HALF + wr * 64 + m * 16 + fr;
;             const f32x4 a0 = *(const f32x4*)(SS2 + (size_t)grow * 8), a1 = *(const f32x4*)(SS2 + (size_t)grow * 8 + 4);
;             const float r2 = rsqrtf(((a0[0] + a0[1]) + (a0[2] + a0[3]) + (a1[0] + a1[1]) + (a1[2] + a1[3])) * (1.f / 2048.f) + EPS);
;             FOR_BJ { acc[ai][bj][m][0] *= r2; acc[ai][bj][m][1] *= r2; } }
;         float tot[2][4][2]; head_ss(acc, tot, X, wr, wc, fr, fq);
.LBB0_879:
	s_or_b64 exec, exec, s[4:5]
	v_mul_f32_e32 v161, 0x4b800000, v160
	v_cndmask_b32_e32 v160, v160, v161, vcc
	v_rsq_f32_e32 v160, v160
	s_nop 0
	v_mul_f32_e32 v161, 0x45800000, v160
	v_cndmask_b32_e32 v160, v160, v161, vcc
	v_pk_mul_f32 v[78:79], v[78:79], v[160:161] op_sel_hi:[1,0]
	v_pk_mul_f32 v[76:77], v[76:77], v[160:161] op_sel_hi:[1,0]
	v_pk_mul_f32 v[74:75], v[74:75], v[160:161] op_sel_hi:[1,0]
	v_pk_mul_f32 v[72:73], v[72:73], v[160:161] op_sel_hi:[1,0]
	v_mul_f32_e32 v161, v77, v77
	s_waitcnt lgkmcnt(0)
	v_mul_f32_e32 v162, v79, v79
	v_fmac_f32_e32 v161, v76, v76
	v_fmac_f32_e32 v162, v78, v78
	v_add_f32_e32 v161, v161, v162
	v_mul_f32_e32 v162, v73, v73
	v_fmac_f32_e32 v162, v72, v72
	v_add_f32_e32 v161, v162, v161
	v_mul_f32_e32 v162, v75, v75
	v_fmac_f32_e32 v162, v74, v74
	v_add_f32_e32 v161, v162, v161
	v_mov_b32_e32 v162, v161
	s_nop 1
	v_permlane16_swap_b32_e32 v162, v161
	s_waitcnt lgkmcnt(0)
	v_add_f32_e32 v161, v161, v162
	v_mov_b32_e32 v162, v161
	s_nop 1
	v_permlane32_swap_b32_e32 v162, v161
	s_and_saveexec_b64 s[4:5], s[0:1]
	s_cbranch_execz .LBB0_881
	s_waitcnt lgkmcnt(0)
	v_add_f32_e32 v161, v161, v162
	ds_write_b32 v223, v161 offset:1536
.LBB0_881:
	s_or_b64 exec, exec, s[4:5]
	v_mov_b32_e32 v161, v160
	s_waitcnt lgkmcnt(0)
	v_mov_b32_e32 v162, v160
	v_mov_b32_e32 v163, v160
	v_pk_mul_f32 v[70:71], v[70:71], v[162:163]
	v_pk_mul_f32 v[68:69], v[68:69], v[160:161]
	v_pk_mul_f32 v[64:65], v[64:65], v[160:161]
	v_mul_f32_e32 v160, v69, v69
	v_mul_f32_e32 v161, v71, v71
	v_fmac_f32_e32 v160, v68, v68
	v_fmac_f32_e32 v161, v70, v70
	v_add_f32_e32 v160, v160, v161
	v_mul_f32_e32 v161, v65, v65
	v_pk_mul_f32 v[66:67], v[66:67], v[162:163]
	v_fmac_f32_e32 v161, v64, v64
	v_add_f32_e32 v160, v161, v160
	v_mul_f32_e32 v161, v67, v67
	v_fmac_f32_e32 v161, v66, v66
	v_add_f32_e32 v160, v161, v160
	v_mov_b32_e32 v161, v160
	s_nop 1
	v_permlane16_swap_b32_e32 v161, v160
	s_waitcnt lgkmcnt(0)
	v_add_f32_e32 v160, v160, v161
	v_mov_b32_e32 v161, v160
	s_nop 1
	v_permlane32_swap_b32_e32 v161, v160
	s_and_saveexec_b64 s[4:5], s[0:1]
	s_cbranch_execz .LBB0_883
	s_waitcnt lgkmcnt(0)
	v_add_f32_e32 v160, v160, v161
	ds_write_b32 v223, v160 offset:1552
.LBB0_883:
	s_or_b64 exec, exec, s[4:5]
	v_mov_b32_e32 v160, v157
	s_waitcnt lgkmcnt(0)
	v_mov_b32_e32 v161, v158
	v_mov_b32_e32 v157, v159
	v_mov_b32_e32 v158, v154
	v_mov_b32_e32 v159, v152
	v_mov_b32_e32 v152, v155
	v_mov_b32_e32 v154, v149
	v_mov_b32_e32 v155, v150
	v_mov_b32_e32 v149, v151
	v_pk_add_f32 v[156:157], v[160:161], v[156:157]
	v_pk_add_f32 v[148:149], v[154:155], v[148:149]
	v_mov_b32_e32 v150, v146
	v_mov_b32_e32 v151, v144
	v_mov_b32_e32 v144, v147
	v_pk_add_f32 v[152:153], v[158:159], v[152:153]
	v_pk_add_f32 v[144:145], v[150:151], v[144:145]
	v_mov_b32_e32 v146, v148
	v_mov_b32_e32 v147, v156
	v_mov_b32_e32 v156, v149
	v_pk_add_f32 v[146:147], v[146:147], v[156:157]
	v_mov_b32_e32 v148, v145
	v_mov_b32_e32 v149, v153
	v_pk_add_f32 v[146:147], v[146:147], v[148:149]
	v_mov_b32_e32 v145, v152
	v_pk_add_f32 v[144:145], v[144:145], v[146:147]
	s_nop 0
	v_pk_fma_f32 v[144:145], v[144:145], s[20:21], v[194:195] op_sel_hi:[1,0,0]
	s_nop 0
	v_mul_f32_e32 v146, 0x4b800000, v145
	v_cmp_gt_f32_e32 vcc, s67, v145
	s_nop 1
	v_cndmask_b32_e32 v145, v145, v146, vcc
	v_rsq_f32_e32 v145, v145
	s_nop 0
	v_mul_f32_e32 v146, 0x45800000, v145
	v_cndmask_b32_e32 v146, v145, v146, vcc
	v_pk_mul_f32 v[62:63], v[62:63], v[146:147] op_sel_hi:[1,0]
	v_pk_mul_f32 v[60:61], v[60:61], v[146:147] op_sel_hi:[1,0]
	v_pk_mul_f32 v[58:59], v[58:59], v[146:147] op_sel_hi:[1,0]
	v_pk_mul_f32 v[56:57], v[56:57], v[146:147] op_sel_hi:[1,0]
	v_mul_f32_e32 v145, v61, v61
	v_mul_f32_e32 v147, v63, v63
	v_fmac_f32_e32 v145, v60, v60
	v_fmac_f32_e32 v147, v62, v62
	v_add_f32_e32 v145, v145, v147
	v_mul_f32_e32 v147, v57, v57
	v_fmac_f32_e32 v147, v56, v56
	v_add_f32_e32 v145, v147, v145
	v_mul_f32_e32 v147, v59, v59
	v_fmac_f32_e32 v147, v58, v58
	v_add_f32_e32 v145, v147, v145
	v_mov_b32_e32 v147, v145
	s_nop 1
	v_permlane16_swap_b32_e32 v147, v145
	v_cmp_gt_f32_e32 vcc, s67, v144
	s_waitcnt lgkmcnt(0)
	v_add_f32_e32 v145, v145, v147
	v_mov_b32_e32 v147, v145
	s_nop 1
	v_permlane32_swap_b32_e32 v147, v145
	s_and_saveexec_b64 s[4:5], s[0:1]
	s_cbranch_execz .LBB0_885
	s_waitcnt lgkmcnt(0)
	v_add_f32_e32 v145, v145, v147
	ds_write_b32 v223, v145 offset:4096
.LBB0_885:
	s_or_b64 exec, exec, s[4:5]
	s_waitcnt lgkmcnt(0)
	v_mov_b32_e32 v147, v146
	v_mov_b32_e32 v148, v146
	v_mov_b32_e32 v149, v146
	v_pk_mul_f32 v[54:55], v[54:55], v[148:149]
	v_pk_mul_f32 v[52:53], v[52:53], v[146:147]
	v_pk_mul_f32 v[48:49], v[48:49], v[146:147]
	v_mul_f32_e32 v145, v53, v53
	v_mul_f32_e32 v146, v55, v55
	v_fmac_f32_e32 v145, v52, v52
	v_fmac_f32_e32 v146, v54, v54
	v_add_f32_e32 v145, v145, v146
	v_mul_f32_e32 v146, v49, v49
	v_pk_mul_f32 v[50:51], v[50:51], v[148:149]
	v_fmac_f32_e32 v146, v48, v48
	v_add_f32_e32 v145, v146, v145
	v_mul_f32_e32 v146, v51, v51
	v_fmac_f32_e32 v146, v50, v50
	v_add_f32_e32 v145, v146, v145
	v_mov_b32_e32 v146, v145
	s_nop 1
	v_permlane16_swap_b32_e32 v146, v145
	s_waitcnt lgkmcnt(0)
	v_add_f32_e32 v145, v145, v146
	v_mov_b32_e32 v146, v145
	s_nop 1
	v_permlane32_swap_b32_e32 v146, v145
	s_and_saveexec_b64 s[4:5], s[0:1]
	s_cbranch_execz .LBB0_887
	s_waitcnt lgkmcnt(0)
	v_add_f32_e32 v145, v145, v146
	ds_write_b32 v223, v145 offset:4112
; #define LAS __attribute__((address_space(3)))
; #define EPI_BAR() do { asm volatile("s_waitcnt lgkmcnt(0)" ::: "memory"); __builtin_amdgcn_s_barrier(); asm volatile("" ::: "memory"); } while (0)
; #define FOR_AI_M _Pragma("unroll") for (int ai = 0; ai < 2; ++ai) _Pragma("unroll") for (int m = 0; m < 4; ++m)
; #define FOR_BJ _Pragma("unroll") for (int bj = 0; bj < 2; ++bj)
; __device__ __forceinline__ void head_ss(const f32x4 (&v)[2][2][4][2], float (&tot)[2][4][2], LAS float* X, int wr, int wc, int fr, int fq) {
; #pragma unroll
;     for (int ai = 0; ai < 2; ++ai)
; #pragma unroll
;         for (int m = 0; m < 4; ++m)
; #pragma unroll
;             for (int bj = 0; bj < 2; ++bj) {
;                 const f32x4 a = v[ai][bj][m][0], b = v[ai][bj][m][1];
;                 float s = (a[0] * a[0] + a[1] * a[1]) + (a[2] * a[2] + a[3] * a[3]) + (b[0] * b[0] + b[1] * b[1]) + (b[2] * b[2] + b[3] * b[3]);
;                 s += __shfl_xor(s, 16); s += __shfl_xor(s, 32);
;                 if (fq == 0) X[((ai * 128 + wr * 64 + m * 16 + fr) * 2 + bj) * 4 + wc] = s;
;             }
;     EPI_BAR();
;     __device__ __forceinline__ void operator()(f32x4 (&acc)[2][2][4][2], const Unit& u, int wr, int wc, int fr, int fq) const {
;         FOR_AI_M { const int grow = u.pm * BM + ai * HALF + wr * 64 + m * 16 + fr;
;             const f32x4 a0 = *(const f32x4*)(SS2 + (size_t)grow * 8), a1 = *(const f32x4*)(SS2 + (size_t)grow * 8 + 4);
;             const float r2 = rsqrtf(((a0[0] + a0[1]) + (a0[2] + a0[3]) + (a1[0] + a1[1]) + (a1[2] + a1[3])) * (1.f / 2048.f) + EPS);
;             FOR_BJ { acc[ai][bj][m][0] *= r2; acc[ai][bj][m][1] *= r2; } }
;         float tot[2][4][2]; head_ss(acc, tot, X, wr, wc, fr, fq);
.LBB0_887:
	s_or_b64 exec, exec, s[4:5]
	v_mul_f32_e32 v145, 0x4b800000, v144
	v_cndmask_b32_e32 v144, v144, v145, vcc
	v_rsq_f32_e32 v144, v144
	s_nop 0
	v_mul_f32_e32 v145, 0x45800000, v144
	v_cndmask_b32_e32 v144, v144, v145, vcc
	v_pk_mul_f32 v[46:47], v[46:47], v[144:145] op_sel_hi:[1,0]
	v_pk_mul_f32 v[44:45], v[44:45], v[144:145] op_sel_hi:[1,0]
	v_pk_mul_f32 v[42:43], v[42:43], v[144:145] op_sel_hi:[1,0]
	v_pk_mul_f32 v[40:41], v[40:41], v[144:145] op_sel_hi:[1,0]
	v_mul_f32_e32 v145, v45, v45
	s_waitcnt lgkmcnt(0)
	v_mul_f32_e32 v146, v47, v47
	v_fmac_f32_e32 v145, v44, v44
	v_fmac_f32_e32 v146, v46, v46
	v_add_f32_e32 v145, v145, v146
	v_mul_f32_e32 v146, v41, v41
	v_fmac_f32_e32 v146, v40, v40
	v_add_f32_e32 v145, v146, v145
	v_mul_f32_e32 v146, v43, v43
	v_fmac_f32_e32 v146, v42, v42
	v_add_f32_e32 v145, v146, v145
	v_mov_b32_e32 v146, v145
	s_nop 1
	v_permlane16_swap_b32_e32 v146, v145
	s_waitcnt lgkmcnt(0)
	v_add_f32_e32 v145, v145, v146
	v_mov_b32_e32 v146, v145
	s_nop 1
	v_permlane32_swap_b32_e32 v146, v145
	s_and_saveexec_b64 s[4:5], s[0:1]
	s_cbranch_execz .LBB0_889
	s_waitcnt lgkmcnt(0)
	v_add_f32_e32 v145, v145, v146
	ds_write_b32 v223, v145 offset:4608
.LBB0_889:
	s_or_b64 exec, exec, s[4:5]
	v_mov_b32_e32 v145, v144
	s_waitcnt lgkmcnt(0)
	v_mov_b32_e32 v146, v144
	v_mov_b32_e32 v147, v144
	v_pk_mul_f32 v[38:39], v[38:39], v[146:147]
	v_pk_mul_f32 v[36:37], v[36:37], v[144:145]
	v_pk_mul_f32 v[32:33], v[32:33], v[144:145]
	v_mul_f32_e32 v144, v37, v37
	v_mul_f32_e32 v145, v39, v39
	v_fmac_f32_e32 v144, v36, v36
	v_fmac_f32_e32 v145, v38, v38
	v_add_f32_e32 v144, v144, v145
	v_mul_f32_e32 v145, v33, v33
	v_pk_mul_f32 v[34:35], v[34:35], v[146:147]
	v_fmac_f32_e32 v145, v32, v32
	v_add_f32_e32 v144, v145, v144
	v_mul_f32_e32 v145, v35, v35
	v_fmac_f32_e32 v145, v34, v34
	v_add_f32_e32 v144, v145, v144
	v_mov_b32_e32 v145, v144
	s_nop 1
	v_permlane16_swap_b32_e32 v145, v144
	s_waitcnt lgkmcnt(0)
	v_add_f32_e32 v144, v144, v145
	v_mov_b32_e32 v145, v144
	s_nop 1
	v_permlane32_swap_b32_e32 v145, v144
	s_and_saveexec_b64 s[4:5], s[0:1]
	s_cbranch_execz .LBB0_891
	s_waitcnt lgkmcnt(0)
	v_add_f32_e32 v144, v144, v145
	ds_write_b32 v223, v144 offset:4624
.LBB0_891:
	s_or_b64 exec, exec, s[4:5]
	v_mov_b32_e32 v144, v141
	s_waitcnt lgkmcnt(0)
	v_mov_b32_e32 v145, v142
	v_mov_b32_e32 v141, v143
	v_mov_b32_e32 v142, v138
	v_mov_b32_e32 v143, v136
	v_mov_b32_e32 v136, v139
	v_mov_b32_e32 v138, v133
	v_mov_b32_e32 v139, v134
	v_mov_b32_e32 v133, v135
	v_pk_add_f32 v[140:141], v[144:145], v[140:141]
	v_pk_add_f32 v[132:133], v[138:139], v[132:133]
	v_mov_b32_e32 v134, v130
	v_mov_b32_e32 v135, v128
	v_mov_b32_e32 v128, v131
	v_pk_add_f32 v[136:137], v[142:143], v[136:137]
	v_pk_add_f32 v[128:129], v[134:135], v[128:129]
	v_mov_b32_e32 v130, v132
	v_mov_b32_e32 v131, v140
	v_mov_b32_e32 v140, v133
	v_pk_add_f32 v[130:131], v[130:131], v[140:141]
	v_mov_b32_e32 v132, v129
	v_mov_b32_e32 v133, v137
	v_pk_add_f32 v[130:131], v[130:131], v[132:133]
	v_mov_b32_e32 v129, v136
	v_pk_add_f32 v[128:129], v[128:129], v[130:131]
	s_nop 0
	v_pk_fma_f32 v[128:129], v[128:129], s[20:21], v[194:195] op_sel_hi:[1,0,0]
	s_nop 0
	v_mul_f32_e32 v130, 0x4b800000, v129
	v_cmp_gt_f32_e32 vcc, s67, v129
	s_nop 1
	v_cndmask_b32_e32 v129, v129, v130, vcc
	v_rsq_f32_e32 v129, v129
	s_nop 0
	v_mul_f32_e32 v130, 0x45800000, v129
	v_cndmask_b32_e32 v130, v129, v130, vcc
	v_pk_mul_f32 v[30:31], v[30:31], v[130:131] op_sel_hi:[1,0]
	v_pk_mul_f32 v[28:29], v[28:29], v[130:131] op_sel_hi:[1,0]
	v_pk_mul_f32 v[26:27], v[26:27], v[130:131] op_sel_hi:[1,0]
	v_pk_mul_f32 v[24:25], v[24:25], v[130:131] op_sel_hi:[1,0]
	v_mul_f32_e32 v129, v29, v29
	v_mul_f32_e32 v131, v31, v31
	v_fmac_f32_e32 v129, v28, v28
	v_fmac_f32_e32 v131, v30, v30
	v_add_f32_e32 v129, v129, v131
	v_mul_f32_e32 v131, v25, v25
	v_fmac_f32_e32 v131, v24, v24
	v_add_f32_e32 v129, v131, v129
	v_mul_f32_e32 v131, v27, v27
	v_fmac_f32_e32 v131, v26, v26
	v_add_f32_e32 v129, v131, v129
	v_mov_b32_e32 v131, v129
	s_nop 1
	v_permlane16_swap_b32_e32 v131, v129
	v_cmp_gt_f32_e32 vcc, s67, v128
	s_waitcnt lgkmcnt(0)
	v_add_f32_e32 v129, v129, v131
	v_mov_b32_e32 v131, v129
	s_nop 1
	v_permlane32_swap_b32_e32 v131, v129
	s_and_saveexec_b64 s[4:5], s[0:1]
	s_cbranch_execz .LBB0_893
	s_waitcnt lgkmcnt(0)
	v_add_f32_e32 v129, v129, v131
	ds_write_b32 v223, v129 offset:5120
; #define FOR_AI_M _Pragma("unroll") for (int ai = 0; ai < 2; ++ai) _Pragma("unroll") for (int m = 0; m < 4; ++m)
; #define FOR_BJ _Pragma("unroll") for (int bj = 0; bj < 2; ++bj)
; __device__ __forceinline__ void head_ss(const f32x4 (&v)[2][2][4][2], float (&tot)[2][4][2], LAS float* X, int wr, int wc, int fr, int fq) {
;     ...
;                 const f32x4 a = v[ai][bj][m][0], b = v[ai][bj][m][1];
;                 float s = (a[0] * a[0] + a[1] * a[1]) + (a[2] * a[2] + a[3] * a[3]) + (b[0] * b[0] + b[1] * b[1]) + (b[2] * b[2] + b[3] * b[3]);
;                 s += __shfl_xor(s, 16); s += __shfl_xor(s, 32);
;                 if (fq == 0) X[((ai * 128 + wr * 64 + m * 16 + fr) * 2 + bj) * 4 + wc] = s;
;     __device__ __forceinline__ void operator()(f32x4 (&acc)[2][2][4][2], const Unit& u, int wr, int wc, int fr, int fq) const {
;         FOR_AI_M { const int grow = u.pm * BM + ai * HALF + wr * 64 + m * 16 + fr;
;             const f32x4 a0 = *(const f32x4*)(SS2 + (size_t)grow * 8), a1 = *(const f32x4*)(SS2 + (size_t)grow * 8 + 4);
;             const float r2 = rsqrtf(((a0[0] + a0[1]) + (a0[2] + a0[3]) + (a1[0] + a1[1]) + (a1[2] + a1[3])) * (1.f / 2048.f) + EPS);
;             FOR_BJ { acc[ai][bj][m][0] *= r2; acc[ai][bj][m][1] *= r2; } }
.LBB0_893:
	s_or_b64 exec, exec, s[4:5]
	s_waitcnt lgkmcnt(0)
	v_mov_b32_e32 v131, v130
	v_mov_b32_e32 v132, v130
	v_mov_b32_e32 v133, v130
	v_pk_mul_f32 v[22:23], v[22:23], v[132:133]
	v_pk_mul_f32 v[20:21], v[20:21], v[130:131]
	v_pk_mul_f32 v[16:17], v[16:17], v[130:131]
	v_mul_f32_e32 v129, v21, v21
	v_mul_f32_e32 v130, v23, v23
	v_fmac_f32_e32 v129, v20, v20
	v_fmac_f32_e32 v130, v22, v22
	v_add_f32_e32 v129, v129, v130
	v_mul_f32_e32 v130, v17, v17
	v_pk_mul_f32 v[18:19], v[18:19], v[132:133]
	v_fmac_f32_e32 v130, v16, v16
	v_add_f32_e32 v129, v130, v129
	v_mul_f32_e32 v130, v19, v19
	v_fmac_f32_e32 v130, v18, v18
	v_add_f32_e32 v129, v130, v129
	v_mov_b32_e32 v130, v129
	s_nop 1
	v_permlane16_swap_b32_e32 v130, v129
	s_waitcnt lgkmcnt(0)
	v_add_f32_e32 v129, v129, v130
	v_mov_b32_e32 v130, v129
	s_nop 1
	v_permlane32_swap_b32_e32 v130, v129
	s_and_saveexec_b64 s[4:5], s[0:1]
	s_cbranch_execz .LBB0_895
	s_waitcnt lgkmcnt(0)
	v_add_f32_e32 v129, v129, v130
	ds_write_b32 v223, v129 offset:5136
.LBB0_895:
	s_or_b64 exec, exec, s[4:5]
	v_mul_f32_e32 v129, 0x4b800000, v128
	v_cndmask_b32_e32 v128, v128, v129, vcc
	v_rsq_f32_e32 v128, v128
	s_nop 0
	v_mul_f32_e32 v129, 0x45800000, v128
	v_cndmask_b32_e32 v140, v128, v129, vcc
	s_waitcnt lgkmcnt(0)
	v_pk_mul_f32 v[130:131], v[14:15], v[140:141] op_sel_hi:[1,0]
	v_pk_mul_f32 v[134:135], v[12:13], v[140:141] op_sel_hi:[1,0]
	v_pk_mul_f32 v[132:133], v[8:9], v[140:141] op_sel_hi:[1,0]
	v_mul_f32_e32 v8, v135, v135
	v_mul_f32_e32 v9, v131, v131
	v_fmac_f32_e32 v8, v134, v134
	v_fmac_f32_e32 v9, v130, v130
	v_add_f32_e32 v8, v8, v9
	v_mul_f32_e32 v9, v133, v133
	v_pk_mul_f32 v[128:129], v[10:11], v[140:141] op_sel_hi:[1,0]
	v_fmac_f32_e32 v9, v132, v132
	v_add_f32_e32 v8, v9, v8
	v_mul_f32_e32 v9, v129, v129
	v_fmac_f32_e32 v9, v128, v128
	v_add_f32_e32 v8, v9, v8
	v_mov_b32_e32 v9, v8
	s_nop 1
	v_permlane16_swap_b32_e32 v9, v8
	s_waitcnt lgkmcnt(0)
	v_add_f32_e32 v8, v8, v9
	v_mov_b32_e32 v9, v8
	s_nop 1
	v_permlane32_swap_b32_e32 v9, v8
	s_and_saveexec_b64 s[4:5], s[0:1]
	s_cbranch_execz .LBB0_897
	s_waitcnt lgkmcnt(0)
	v_add_f32_e32 v8, v8, v9
	ds_write_b32 v223, v8 offset:5632
.LBB0_897:
	s_or_b64 exec, exec, s[4:5]
	v_mov_b32_e32 v141, v140
	v_mov_b32_e32 v8, v140
	s_waitcnt lgkmcnt(0)
	v_mov_b32_e32 v9, v140
	v_pk_mul_f32 v[138:139], v[6:7], v[8:9]
	v_pk_mul_f32 v[142:143], v[4:5], v[140:141]
	v_pk_mul_f32 v[140:141], v[0:1], v[140:141]
	v_mul_f32_e32 v0, v143, v143
	v_mul_f32_e32 v1, v139, v139
	v_fmac_f32_e32 v0, v142, v142
	v_fmac_f32_e32 v1, v138, v138
	v_add_f32_e32 v0, v0, v1
	v_mul_f32_e32 v1, v141, v141
	v_pk_mul_f32 v[136:137], v[2:3], v[8:9]
	v_fmac_f32_e32 v1, v140, v140
	v_add_f32_e32 v0, v1, v0
	v_mul_f32_e32 v1, v137, v137
	v_fmac_f32_e32 v1, v136, v136
	v_add_f32_e32 v0, v1, v0
	v_mov_b32_e32 v1, v0
	s_nop 1
	v_permlane16_swap_b32_e32 v1, v0
	s_waitcnt lgkmcnt(0)
	v_add_f32_e32 v0, v0, v1
	v_mov_b32_e32 v1, v0
	s_nop 1
	v_permlane32_swap_b32_e32 v1, v0
	s_and_saveexec_b64 s[4:5], s[0:1]
	s_cbranch_execz .LBB0_899
	s_waitcnt lgkmcnt(0)
	v_add_f32_e32 v0, v0, v1
	ds_write_b32 v223, v0 offset:5648

; __device__ __forceinline__ u32x4 pack8(f32x4 a, f32x4 b) { u32x4 w; w.x = cvtpk(a[0], a[1]); w.y = cvtpk(a[2], a[3]); w.z = cvtpk(b[0], b[1]); w.w = cvtpk(b[2], b[3]); return w; }
; #define FOR_BJ _Pragma("unroll") for (int bj = 0; bj < 2; ++bj)
;     __device__ __forceinline__ void operator()(f32x4 (&acc)[2][2][4][2], const Unit& u, int wr, int wc, int fr, int fq) const {
; #pragma unroll
;         for (int ai = 0; ai < 2; ++ai) {
;             u32x4 hr[4][2];
; #pragma unroll
;             for (int m = 0; m < 4; ++m) FOR_BJ { const unsigned off = (unsigned)(u.pm * BM + ai * HALF + wr * 64 + m * 16 + fr) * DM + u.pn * BM + 128 * bj + 32 * wc + 8 * fq; hr[m][bj] = *(const u32x4*)(H2B + off); }
; #pragma unroll
;             for (int m = 0; m < 4; ++m) FOR_BJ { const unsigned off = (unsigned)(u.pm * BM + ai * HALF + wr * 64 + m * 16 + fr) * DM + u.pn * BM + 128 * bj + 32 * wc + 8 * fq;
;                 const u32x4 h = hr[m][bj];
;                 const f32x4 v0 = acc[ai][bj][m][0] + (f32x4){bflo(h.x), bfhi(h.x), bflo(h.y), bfhi(h.y)}, v1 = acc[ai][bj][m][1] + (f32x4){bflo(h.z), bfhi(h.z), bflo(h.w), bfhi(h.w)};
;                 acc[ai][bj][m][0] = v0; acc[ai][bj][m][1] = v1;
;                 *(u32x4*)(H2B + off) = pack8(v0, v1); }
;             asm volatile("" ::: "memory");
.LBB0_1049:
	v_lshl_add_u32 v146, s42, 8, v160
	v_lshl_or_b32 v128, s8, 8, v162
	v_lshl_add_u32 v140, v146, 11, v128
	s_waitcnt vmcnt(0)
	v_lshl_add_u64 v[192:193], v[140:141], 1, s[88:89]
	v_mov_b32_e32 v129, v141
	v_or_b32_e32 v128, 0x80, v140
	global_load_dwordx4 v[148:151], v[192:193], off
	v_lshl_add_u64 v[194:195], v[128:129], 1, s[88:89]
	v_add_u32_e32 v128, 0x8000, v140
	global_load_dwordx4 v[152:155], v[194:195], off
	v_lshl_add_u64 v[196:197], v[128:129], 1, s[88:89]
	global_load_dwordx4 v[168:171], v[196:197], off
	v_add_u32_e32 v128, 0x8080, v140
	v_lshl_add_u64 v[198:199], v[128:129], 1, s[88:89]
	global_load_dwordx4 v[172:175], v[198:199], off
	v_add_u32_e32 v128, 0x10000, v140
	v_lshl_add_u64 v[200:201], v[128:129], 1, s[88:89]
	global_load_dwordx4 v[180:183], v[200:201], off
	v_mov_b32_e32 v131, v141
	v_add_u32_e32 v130, 0x10080, v140
	v_mov_b32_e32 v157, v141
	v_add_u32_e32 v128, 0x18000, v140
	v_add_u32_e32 v156, 0x18080, v140
	v_lshl_add_u64 v[202:203], v[130:131], 1, s[88:89]
	v_lshl_add_u64 v[158:159], v[128:129], 1, s[88:89]
	v_lshl_add_u64 v[156:157], v[156:157], 1, s[88:89]
	global_load_dwordx4 v[184:187], v[202:203], off
	global_load_dwordx4 v[188:191], v[158:159], off
	global_load_dwordx4 v[128:131], v[156:157], off
	s_waitcnt vmcnt(0)
	v_lshlrev_b32_e32 v204, 16, v148
	v_and_b32_e32 v205, 0xffff0000, v148
	v_lshlrev_b32_e32 v148, 16, v149
	v_and_b32_e32 v149, 0xffff0000, v149
	v_lshlrev_b32_e32 v206, 16, v150
	v_and_b32_e32 v207, 0xffff0000, v150
	v_lshlrev_b32_e32 v150, 16, v151
	v_and_b32_e32 v151, 0xffff0000, v151
	v_pk_add_f32 v[126:127], v[126:127], v[148:149]
	v_pk_add_f32 v[124:125], v[124:125], v[204:205]
	v_pk_add_f32 v[122:123], v[122:123], v[150:151]
	v_pk_add_f32 v[120:121], v[120:121], v[206:207]
	v_lshlrev_b32_e32 v148, 16, v152
	v_and_b32_e32 v149, 0xffff0000, v152
	v_lshlrev_b32_e32 v150, 16, v153
	v_and_b32_e32 v151, 0xffff0000, v153
	v_lshlrev_b32_e32 v204, 16, v154
	v_and_b32_e32 v205, 0xffff0000, v154
	v_lshlrev_b32_e32 v206, 16, v155
	v_and_b32_e32 v207, 0xffff0000, v155
	v_lshlrev_b32_e32 v208, 16, v168
	v_and_b32_e32 v209, 0xffff0000, v168
	v_lshlrev_b32_e32 v210, 16, v169
	v_and_b32_e32 v211, 0xffff0000, v169
	v_lshlrev_b32_e32 v212, 16, v170
	v_and_b32_e32 v213, 0xffff0000, v170
	v_lshlrev_b32_e32 v214, 16, v171
	v_and_b32_e32 v215, 0xffff0000, v171
	v_pk_add_f32 v[152:153], v[110:111], v[150:151]
	v_pk_add_f32 v[154:155], v[108:109], v[148:149]
	v_pk_add_f32 v[148:149], v[106:107], v[206:207]
	v_pk_add_f32 v[150:151], v[104:105], v[204:205]
	v_cvt_pk_bf16_f32 v168, v124, v125
	v_cvt_pk_bf16_f32 v169, v126, v127
	v_cvt_pk_bf16_f32 v170, v120, v121
	v_cvt_pk_bf16_f32 v171, v122, v123
	v_pk_add_f32 v[108:109], v[118:119], v[210:211]
	v_pk_add_f32 v[116:117], v[116:117], v[208:209]
	v_pk_add_f32 v[104:105], v[114:115], v[214:215]
	v_pk_add_f32 v[106:107], v[112:113], v[212:213]
	v_cvt_pk_bf16_f32 v110, v154, v155
	v_cvt_pk_bf16_f32 v111, v152, v153
	v_cvt_pk_bf16_f32 v112, v150, v151
	v_cvt_pk_bf16_f32 v113, v148, v149
	v_lshlrev_b32_e32 v216, 16, v172
	v_and_b32_e32 v217, 0xffff0000, v172
	v_lshlrev_b32_e32 v172, 16, v173
	global_store_dwordx4 v[192:193], v[168:171], off
	v_and_b32_e32 v173, 0xffff0000, v173
	v_pk_add_f32 v[102:103], v[102:103], v[172:173]
	v_cvt_pk_bf16_f32 v168, v116, v117
	v_cvt_pk_bf16_f32 v169, v108, v109
	v_cvt_pk_bf16_f32 v170, v106, v107
	v_cvt_pk_bf16_f32 v171, v104, v105
	global_store_dwordx4 v[194:195], v[110:113], off
	global_store_dwordx4 v[196:197], v[168:171], off
	v_pk_add_f32 v[100:101], v[100:101], v[216:217]
	v_lshlrev_b32_e32 v110, 16, v174
	v_and_b32_e32 v111, 0xffff0000, v174
	v_lshlrev_b32_e32 v112, 16, v175
	v_and_b32_e32 v113, 0xffff0000, v175
	v_pk_add_f32 v[94:95], v[94:95], v[112:113]
	v_pk_add_f32 v[110:111], v[92:93], v[110:111]
	v_cvt_pk_bf16_f32 v112, v100, v101
	v_cvt_pk_bf16_f32 v113, v102, v103
	v_cvt_pk_bf16_f32 v114, v110, v111
	v_cvt_pk_bf16_f32 v115, v94, v95
	global_store_dwordx4 v[198:199], v[112:115], off
	v_lshlrev_b32_e32 v92, 16, v181
	v_and_b32_e32 v93, 0xffff0000, v181
	v_lshlrev_b32_e32 v112, 16, v180
	v_and_b32_e32 v113, 0xffff0000, v180
	v_pk_add_f32 v[92:93], v[98:99], v[92:93]
	v_pk_add_f32 v[96:97], v[96:97], v[112:113]
	v_lshlrev_b32_e32 v98, 16, v182
	v_and_b32_e32 v99, 0xffff0000, v182
	v_lshlrev_b32_e32 v112, 16, v183
	v_and_b32_e32 v113, 0xffff0000, v183
	v_pk_add_f32 v[90:91], v[90:91], v[112:113]
	v_pk_add_f32 v[88:89], v[88:89], v[98:99]
	v_cvt_pk_bf16_f32 v112, v96, v97
	v_cvt_pk_bf16_f32 v113, v92, v93
	v_cvt_pk_bf16_f32 v114, v88, v89
	v_cvt_pk_bf16_f32 v115, v90, v91
	global_store_dwordx4 v[200:201], v[112:115], off
	v_lshlrev_b32_e32 v98, 16, v184
	v_and_b32_e32 v99, 0xffff0000, v184
	v_lshlrev_b32_e32 v112, 16, v185
	v_and_b32_e32 v113, 0xffff0000, v185
	v_pk_add_f32 v[86:87], v[86:87], v[112:113]
	v_pk_add_f32 v[84:85], v[84:85], v[98:99]
	v_lshlrev_b32_e32 v98, 16, v186
	v_and_b32_e32 v99, 0xffff0000, v186
	v_lshlrev_b32_e32 v112, 16, v187
	v_and_b32_e32 v113, 0xffff0000, v187
	v_pk_add_f32 v[78:79], v[78:79], v[112:113]
	v_pk_add_f32 v[98:99], v[76:77], v[98:99]
	v_cvt_pk_bf16_f32 v112, v84, v85
	v_cvt_pk_bf16_f32 v113, v86, v87
	v_cvt_pk_bf16_f32 v114, v98, v99
	v_cvt_pk_bf16_f32 v115, v78, v79
	global_store_dwordx4 v[202:203], v[112:115], off
	v_lshlrev_b32_e32 v76, 16, v189
	v_and_b32_e32 v77, 0xffff0000, v189
	v_lshlrev_b32_e32 v112, 16, v188
	v_and_b32_e32 v113, 0xffff0000, v188
	v_pk_add_f32 v[76:77], v[82:83], v[76:77]
	v_pk_add_f32 v[80:81], v[80:81], v[112:113]
	v_lshlrev_b32_e32 v82, 16, v190
	v_and_b32_e32 v83, 0xffff0000, v190
	v_lshlrev_b32_e32 v112, 16, v191
	v_and_b32_e32 v113, 0xffff0000, v191
; __device__ __forceinline__ u32x4 pack8(f32x4 a, f32x4 b) { u32x4 w; w.x = cvtpk(a[0], a[1]); w.y = cvtpk(a[2], a[3]); w.z = cvtpk(b[0], b[1]); w.w = cvtpk(b[2], b[3]); return w; }
; #define FOR_BJ _Pragma("unroll") for (int bj = 0; bj < 2; ++bj)
;     __device__ __forceinline__ void operator()(f32x4 (&acc)[2][2][4][2], const Unit& u, int wr, int wc, int fr, int fq) const {
; #pragma unroll
;         for (int ai = 0; ai < 2; ++ai) {
;             u32x4 hr[4][2];
; #pragma unroll
;             for (int m = 0; m < 4; ++m) FOR_BJ { const unsigned off = (unsigned)(u.pm * BM + ai * HALF + wr * 64 + m * 16 + fr) * DM + u.pn * BM + 128 * bj + 32 * wc + 8 * fq; hr[m][bj] = *(const u32x4*)(H2B + off); }
; #pragma unroll
;             for (int m = 0; m < 4; ++m) FOR_BJ { const unsigned off = (unsigned)(u.pm * BM + ai * HALF + wr * 64 + m * 16 + fr) * DM + u.pn * BM + 128 * bj + 32 * wc + 8 * fq;
;                 const u32x4 h = hr[m][bj];
;                 const f32x4 v0 = acc[ai][bj][m][0] + (f32x4){bflo(h.x), bfhi(h.x), bflo(h.y), bfhi(h.y)}, v1 = acc[ai][bj][m][1] + (f32x4){bflo(h.z), bfhi(h.z), bflo(h.w), bfhi(h.w)};
;                 acc[ai][bj][m][0] = v0; acc[ai][bj][m][1] = v1;
;                 *(u32x4*)(H2B + off) = pack8(v0, v1); }
;             asm volatile("" ::: "memory");
	v_pk_add_f32 v[74:75], v[74:75], v[112:113]
	v_pk_add_f32 v[72:73], v[72:73], v[82:83]
	v_cvt_pk_bf16_f32 v112, v80, v81
	v_cvt_pk_bf16_f32 v113, v76, v77
	v_cvt_pk_bf16_f32 v114, v72, v73
	v_cvt_pk_bf16_f32 v115, v74, v75
	global_store_dwordx4 v[158:159], v[112:115], off
	v_lshlrev_b32_e32 v82, 16, v128
	v_and_b32_e32 v83, 0xffff0000, v128
	v_lshlrev_b32_e32 v112, 16, v129
	v_and_b32_e32 v113, 0xffff0000, v129
	v_pk_add_f32 v[70:71], v[70:71], v[112:113]
	v_pk_add_f32 v[68:69], v[68:69], v[82:83]
	v_lshlrev_b32_e32 v82, 16, v130
	v_and_b32_e32 v83, 0xffff0000, v130
	v_lshlrev_b32_e32 v112, 16, v131
	v_and_b32_e32 v113, 0xffff0000, v131
	v_pk_add_f32 v[66:67], v[66:67], v[112:113]
	v_pk_add_f32 v[64:65], v[64:65], v[82:83]
	v_cvt_pk_bf16_f32 v112, v68, v69
	v_cvt_pk_bf16_f32 v113, v70, v71
	v_cvt_pk_bf16_f32 v114, v64, v65
	v_cvt_pk_bf16_f32 v115, v66, v67
	global_store_dwordx4 v[156:157], v[112:115], off
	v_add_u32_e32 v82, 0x40000, v140
	v_mov_b32_e32 v83, v141
	v_lshl_add_u64 v[82:83], v[82:83], 1, s[88:89]
	global_load_dwordx4 v[128:131], v[82:83], off
	v_add_u32_e32 v112, 0x40080, v140
	v_mov_b32_e32 v113, v141
	v_lshl_add_u64 v[114:115], v[112:113], 1, s[88:89]
	global_load_dwordx4 v[156:159], v[114:115], off
	v_add_u32_e32 v112, 0x48000, v140
	v_lshl_add_u64 v[118:119], v[112:113], 1, s[88:89]
	global_load_dwordx4 v[168:171], v[118:119], off
	v_add_u32_e32 v112, 0x48080, v140
	v_lshl_add_u64 v[196:197], v[112:113], 1, s[88:89]
	global_load_dwordx4 v[172:175], v[196:197], off
	v_add_u32_e32 v112, 0x50000, v140
	v_lshl_add_u64 v[198:199], v[112:113], 1, s[88:89]
	global_load_dwordx4 v[180:183], v[198:199], off
	v_add_u32_e32 v112, 0x50080, v140
	v_lshl_add_u64 v[200:201], v[112:113], 1, s[88:89]
	global_load_dwordx4 v[184:187], v[200:201], off
	v_add_u32_e32 v112, 0x58000, v140
	v_lshl_add_u64 v[202:203], v[112:113], 1, s[88:89]
	v_add_u32_e32 v140, 0x58080, v140
	v_lshl_add_u64 v[112:113], v[140:141], 1, s[88:89]
	global_load_dwordx4 v[188:191], v[202:203], off
	global_load_dwordx4 v[192:195], v[112:113], off
	s_waitcnt vmcnt(7)
	v_lshlrev_b32_e32 v204, 16, v128
	v_and_b32_e32 v205, 0xffff0000, v128
	v_lshlrev_b32_e32 v128, 16, v129
	v_and_b32_e32 v129, 0xffff0000, v129
	v_pk_add_f32 v[62:63], v[62:63], v[128:129]
	v_lshlrev_b32_e32 v128, 16, v130
	v_and_b32_e32 v129, 0xffff0000, v130
	v_lshlrev_b32_e32 v130, 16, v131
	v_and_b32_e32 v131, 0xffff0000, v131
	v_pk_add_f32 v[60:61], v[60:61], v[204:205]
	v_pk_add_f32 v[58:59], v[58:59], v[130:131]
	v_pk_add_f32 v[56:57], v[56:57], v[128:129]
	v_cvt_pk_bf16_f32 v128, v60, v61
	v_cvt_pk_bf16_f32 v129, v62, v63
	v_cvt_pk_bf16_f32 v130, v56, v57
	v_cvt_pk_bf16_f32 v131, v58, v59
	global_store_dwordx4 v[82:83], v[128:131], off
	s_waitcnt vmcnt(7)
	v_lshlrev_b32_e32 v82, 16, v156
	v_and_b32_e32 v83, 0xffff0000, v156
	v_lshlrev_b32_e32 v128, 16, v157
	v_and_b32_e32 v129, 0xffff0000, v157
	v_pk_add_f32 v[54:55], v[54:55], v[128:129]
	v_pk_add_f32 v[52:53], v[52:53], v[82:83]
	v_lshlrev_b32_e32 v82, 16, v158
	v_and_b32_e32 v83, 0xffff0000, v158
	v_lshlrev_b32_e32 v128, 16, v159
	v_and_b32_e32 v129, 0xffff0000, v159
	v_pk_add_f32 v[46:47], v[46:47], v[128:129]
	v_pk_add_f32 v[82:83], v[44:45], v[82:83]
	v_cvt_pk_bf16_f32 v128, v52, v53
	v_cvt_pk_bf16_f32 v129, v54, v55
	v_cvt_pk_bf16_f32 v130, v82, v83
	v_cvt_pk_bf16_f32 v131, v46, v47
	global_store_dwordx4 v[114:115], v[128:131], off
	s_waitcnt vmcnt(7)
	v_lshlrev_b32_e32 v114, 16, v168
	v_and_b32_e32 v115, 0xffff0000, v168
	v_lshlrev_b32_e32 v44, 16, v169
	v_and_b32_e32 v45, 0xffff0000, v169
	v_pk_add_f32 v[44:45], v[50:51], v[44:45]
	v_pk_add_f32 v[48:49], v[48:49], v[114:115]
	v_lshlrev_b32_e32 v50, 16, v170
	v_and_b32_e32 v51, 0xffff0000, v170
	v_lshlrev_b32_e32 v114, 16, v171
	v_and_b32_e32 v115, 0xffff0000, v171
	v_pk_add_f32 v[42:43], v[42:43], v[114:115]
	v_pk_add_f32 v[40:41], v[40:41], v[50:51]
	s_waitcnt vmcnt(6)
	v_lshlrev_b32_e32 v50, 16, v172
	v_and_b32_e32 v51, 0xffff0000, v172
	v_lshlrev_b32_e32 v114, 16, v173
	v_and_b32_e32 v115, 0xffff0000, v173
	v_pk_add_f32 v[38:39], v[38:39], v[114:115]
	v_pk_add_f32 v[36:37], v[36:37], v[50:51]
	v_lshlrev_b32_e32 v50, 16, v174
	v_and_b32_e32 v51, 0xffff0000, v174
	v_lshlrev_b32_e32 v114, 16, v175
	v_and_b32_e32 v115, 0xffff0000, v175
	v_pk_add_f32 v[30:31], v[30:31], v[114:115]
	v_pk_add_f32 v[50:51], v[28:29], v[50:51]
	s_waitcnt vmcnt(5)
	v_lshlrev_b32_e32 v114, 16, v180
	v_and_b32_e32 v115, 0xffff0000, v180
	v_lshlrev_b32_e32 v28, 16, v181
	v_and_b32_e32 v29, 0xffff0000, v181
	v_pk_add_f32 v[28:29], v[34:35], v[28:29]
	v_pk_add_f32 v[32:33], v[32:33], v[114:115]
	v_lshlrev_b32_e32 v34, 16, v182
	v_and_b32_e32 v35, 0xffff0000, v182
	v_lshlrev_b32_e32 v114, 16, v183
	v_and_b32_e32 v115, 0xffff0000, v183
	v_pk_add_f32 v[26:27], v[26:27], v[114:115]
	v_pk_add_f32 v[24:25], v[24:25], v[34:35]
	s_waitcnt vmcnt(4)
	v_lshlrev_b32_e32 v34, 16, v184
	v_and_b32_e32 v35, 0xffff0000, v184
	v_lshlrev_b32_e32 v114, 16, v185
	v_and_b32_e32 v115, 0xffff0000, v185
	v_pk_add_f32 v[22:23], v[22:23], v[114:115]
	v_pk_add_f32 v[20:21], v[20:21], v[34:35]
	v_lshlrev_b32_e32 v34, 16, v186
	v_and_b32_e32 v35, 0xffff0000, v186
	v_lshlrev_b32_e32 v114, 16, v187
	v_and_b32_e32 v115, 0xffff0000, v187
	v_cvt_pk_bf16_f32 v128, v48, v49
	v_cvt_pk_bf16_f32 v129, v44, v45
	v_cvt_pk_bf16_f32 v130, v40, v41
	v_cvt_pk_bf16_f32 v131, v42, v43
	v_pk_add_f32 v[14:15], v[14:15], v[114:115]
	v_pk_add_f32 v[34:35], v[12:13], v[34:35]
	s_waitcnt vmcnt(3)
; __device__ __forceinline__ u32x4 pack8(f32x4 a, f32x4 b) { u32x4 w; w.x = cvtpk(a[0], a[1]); w.y = cvtpk(a[2], a[3]); w.z = cvtpk(b[0], b[1]); w.w = cvtpk(b[2], b[3]); return w; }
; #define FOR_BJ _Pragma("unroll") for (int bj = 0; bj < 2; ++bj)
; __device__ __forceinline__ void head_ss(const f32x4 (&v)[2][2][4][2], float (&tot)[2][4][2], LAS float* X, int wr, int wc, int fr, int fq) {
;     ...
;                 const f32x4 a = v[ai][bj][m][0], b = v[ai][bj][m][1];
;                 float s = (a[0] * a[0] + a[1] * a[1]) + (a[2] * a[2] + a[3] * a[3]) + (b[0] * b[0] + b[1] * b[1]) + (b[2] * b[2] + b[3] * b[3]);
;                 s += __shfl_xor(s, 16); s += __shfl_xor(s, 32);
;                 if (fq == 0) X[((ai * 128 + wr * 64 + m * 16 + fr) * 2 + bj) * 4 + wc] = s;
;     __device__ __forceinline__ void operator()(f32x4 (&acc)[2][2][4][2], const Unit& u, int wr, int wc, int fr, int fq) const {
;     ...
;             for (int m = 0; m < 4; ++m) FOR_BJ { const unsigned off = (unsigned)(u.pm * BM + ai * HALF + wr * 64 + m * 16 + fr) * DM + u.pn * BM + 128 * bj + 32 * wc + 8 * fq;
;                 const u32x4 h = hr[m][bj];
;                 const f32x4 v0 = acc[ai][bj][m][0] + (f32x4){bflo(h.x), bfhi(h.x), bflo(h.y), bfhi(h.y)}, v1 = acc[ai][bj][m][1] + (f32x4){bflo(h.z), bfhi(h.z), bflo(h.w), bfhi(h.w)};
;                 acc[ai][bj][m][0] = v0; acc[ai][bj][m][1] = v1;
;                 *(u32x4*)(H2B + off) = pack8(v0, v1); }
;             asm volatile("" ::: "memory");
	v_lshlrev_b32_e32 v114, 16, v188
	v_and_b32_e32 v115, 0xffff0000, v188
	v_lshlrev_b32_e32 v12, 16, v189
	v_and_b32_e32 v13, 0xffff0000, v189
	global_store_dwordx4 v[118:119], v[128:131], off
	v_pk_add_f32 v[12:13], v[18:19], v[12:13]
	v_pk_add_f32 v[16:17], v[16:17], v[114:115]
	v_cvt_pk_bf16_f32 v128, v36, v37
	v_cvt_pk_bf16_f32 v129, v38, v39
	v_cvt_pk_bf16_f32 v130, v50, v51
	v_cvt_pk_bf16_f32 v131, v30, v31
	v_lshlrev_b32_e32 v18, 16, v190
	v_and_b32_e32 v19, 0xffff0000, v190
	v_lshlrev_b32_e32 v114, 16, v191
	v_and_b32_e32 v115, 0xffff0000, v191
	global_store_dwordx4 v[196:197], v[128:131], off
	v_pk_add_f32 v[10:11], v[10:11], v[114:115]
	v_pk_add_f32 v[8:9], v[8:9], v[18:19]
	v_cvt_pk_bf16_f32 v128, v32, v33
	v_cvt_pk_bf16_f32 v129, v28, v29
	v_cvt_pk_bf16_f32 v130, v24, v25
	v_cvt_pk_bf16_f32 v131, v26, v27
	s_waitcnt vmcnt(4)
	v_lshlrev_b32_e32 v18, 16, v192
	v_and_b32_e32 v19, 0xffff0000, v192
	v_lshlrev_b32_e32 v114, 16, v193
	v_and_b32_e32 v115, 0xffff0000, v193
	global_store_dwordx4 v[198:199], v[128:131], off
	v_pk_add_f32 v[6:7], v[6:7], v[114:115]
	v_pk_add_f32 v[4:5], v[4:5], v[18:19]
	v_cvt_pk_bf16_f32 v128, v20, v21
	v_cvt_pk_bf16_f32 v129, v22, v23
	v_cvt_pk_bf16_f32 v130, v34, v35
	v_cvt_pk_bf16_f32 v131, v14, v15
	v_lshlrev_b32_e32 v18, 16, v194
	v_and_b32_e32 v19, 0xffff0000, v194
	v_lshlrev_b32_e32 v114, 16, v195
	v_and_b32_e32 v115, 0xffff0000, v195
	global_store_dwordx4 v[200:201], v[128:131], off
	v_pk_add_f32 v[2:3], v[2:3], v[114:115]
	v_pk_add_f32 v[0:1], v[0:1], v[18:19]
	v_cvt_pk_bf16_f32 v128, v16, v17
	v_cvt_pk_bf16_f32 v129, v12, v13
	v_cvt_pk_bf16_f32 v130, v8, v9
	v_cvt_pk_bf16_f32 v131, v10, v11
	global_store_dwordx4 v[202:203], v[128:131], off
	v_and_b32_e32 v19, 64, v167
	v_xor_b32_e32 v18, 16, v167
	v_cvt_pk_bf16_f32 v128, v4, v5
	v_cvt_pk_bf16_f32 v129, v6, v7
	v_cvt_pk_bf16_f32 v130, v0, v1
	v_cvt_pk_bf16_f32 v131, v2, v3
	global_store_dwordx4 v[112:113], v[128:131], off
	v_mul_f32_e32 v112, v125, v125
	v_mul_f32_e32 v113, v127, v127
	v_fmac_f32_e32 v112, v124, v124
	v_fmac_f32_e32 v113, v126, v126
	v_add_f32_e32 v112, v112, v113
	v_mul_f32_e32 v113, v121, v121
	v_add_u32_e32 v19, 64, v19
	v_fmac_f32_e32 v113, v120, v120
	v_cmp_lt_i32_e32 vcc, v18, v19
	v_add_f32_e32 v112, v113, v112
	v_mul_f32_e32 v113, v123, v123
	v_cndmask_b32_e32 v18, v167, v18, vcc
	v_fmac_f32_e32 v113, v122, v122
	v_lshlrev_b32_e32 v18, 2, v18
	v_add_f32_e32 v113, v113, v112
	v_mov_b32_e32 v114, v113
	s_nop 1
	v_permlane16_swap_b32_e32 v114, v113
	v_xor_b32_e32 v112, 32, v167
	v_cmp_lt_i32_e32 vcc, v112, v19
	s_waitcnt lgkmcnt(0)
	v_add_f32_e32 v113, v113, v114
	v_cndmask_b32_e32 v19, v167, v112, vcc
	v_lshlrev_b32_e32 v112, 2, v19
	v_mov_b32_e32 v114, v113
	s_nop 1
	v_permlane32_swap_b32_e32 v114, v113
	v_add_u32_e32 v19, s58, v163
	s_and_saveexec_b64 s[42:43], s[0:1]
	s_cbranch_execz .LBB0_1051
	s_waitcnt lgkmcnt(0)
	v_add_f32_e32 v113, v113, v114
	ds_write_b32 v19, v113
.LBB0_1051:
	s_or_b64 exec, exec, s[42:43]
	v_mul_f32_e32 v113, v155, v155
	s_waitcnt lgkmcnt(0)
	v_mul_f32_e32 v114, v153, v153
	v_fmac_f32_e32 v113, v154, v154
	v_fmac_f32_e32 v114, v152, v152
	v_add_f32_e32 v113, v113, v114
	v_mul_f32_e32 v114, v151, v151
	v_fmac_f32_e32 v114, v150, v150
	v_add_f32_e32 v113, v114, v113
	v_mul_f32_e32 v114, v149, v149
	v_fmac_f32_e32 v114, v148, v148
	v_add_f32_e32 v113, v114, v113
	v_mov_b32_e32 v114, v113
	s_nop 1
	v_permlane16_swap_b32_e32 v114, v113
	s_waitcnt lgkmcnt(0)
	v_add_f32_e32 v113, v113, v114
	v_mov_b32_e32 v114, v113
	s_nop 1
	v_permlane32_swap_b32_e32 v114, v113
	s_and_saveexec_b64 s[42:43], s[0:1]
	s_cbranch_execz .LBB0_1053
	s_waitcnt lgkmcnt(0)
	v_add_f32_e32 v113, v113, v114
	ds_write_b32 v19, v113 offset:16
.LBB0_1053:
	s_or_b64 exec, exec, s[42:43]
	v_mul_f32_e32 v113, v117, v117
	v_mul_f32_e32 v109, v109, v109
	v_fmac_f32_e32 v113, v116, v116
	v_fmac_f32_e32 v109, v108, v108
	v_mul_f32_e32 v107, v107, v107
	v_add_f32_e32 v108, v113, v109
	v_fmac_f32_e32 v107, v106, v106
	v_mul_f32_e32 v105, v105, v105
	v_add_f32_e32 v106, v107, v108
	v_fmac_f32_e32 v105, v104, v104
	v_add_f32_e32 v104, v105, v106
	v_mov_b32_e32 v105, v104
	s_nop 1
	v_permlane16_swap_b32_e32 v105, v104
	s_waitcnt lgkmcnt(0)
	v_add_f32_e32 v104, v104, v105
	v_mov_b32_e32 v105, v104
	s_nop 1
	v_permlane32_swap_b32_e32 v105, v104
	s_and_saveexec_b64 s[42:43], s[0:1]
	s_cbranch_execz .LBB0_1055
	s_waitcnt lgkmcnt(0)
	v_add_f32_e32 v104, v104, v105
	ds_write_b32 v19, v104 offset:512
.LBB0_1055:
	s_or_b64 exec, exec, s[42:43]
	v_mul_f32_e32 v101, v101, v101
	v_fmac_f32_e32 v101, v100, v100
	v_mul_f32_e32 v100, v103, v103
	v_fmac_f32_e32 v100, v102, v102
	v_add_f32_e32 v100, v101, v100
	v_mul_f32_e32 v101, v111, v111
	v_fmac_f32_e32 v101, v110, v110
	v_mul_f32_e32 v95, v95, v95
	v_add_f32_e32 v100, v101, v100
	v_fmac_f32_e32 v95, v94, v94
	v_add_f32_e32 v94, v95, v100
	v_mov_b32_e32 v95, v94
	s_nop 1
	v_permlane16_swap_b32_e32 v95, v94
	s_waitcnt lgkmcnt(0)
	v_add_f32_e32 v94, v94, v95
	v_mov_b32_e32 v95, v94
	s_nop 1
	v_permlane32_swap_b32_e32 v95, v94
	s_and_saveexec_b64 s[42:43], s[0:1]
	s_cbranch_execz .LBB0_1057
	s_waitcnt lgkmcnt(0)
	v_add_f32_e32 v94, v94, v95
	ds_write_b32 v19, v94 offset:528
.LBB0_1057:
	s_or_b64 exec, exec, s[42:43]
	v_mul_f32_e32 v94, v97, v97
	v_mul_f32_e32 v93, v93, v93
	v_fmac_f32_e32 v94, v96, v96
	v_fmac_f32_e32 v93, v92, v92
	v_mul_f32_e32 v89, v89, v89
	v_add_f32_e32 v92, v94, v93
	v_fmac_f32_e32 v89, v88, v88
	v_add_f32_e32 v88, v89, v92
	v_mul_f32_e32 v89, v91, v91
	v_fmac_f32_e32 v89, v90, v90
	v_add_f32_e32 v88, v89, v88
	v_mov_b32_e32 v89, v88
	s_nop 1
	v_permlane16_swap_b32_e32 v89, v88
	s_waitcnt lgkmcnt(0)
	v_add_f32_e32 v88, v88, v89
	v_mov_b32_e32 v89, v88
	s_nop 1
	v_permlane32_swap_b32_e32 v89, v88
	s_and_saveexec_b64 s[42:43], s[0:1]
	s_cbranch_execz .LBB0_1059
	s_waitcnt lgkmcnt(0)
	v_add_f32_e32 v88, v88, v89
	ds_write_b32 v19, v88 offset:1024
; __device__ __forceinline__ void head_ss(const f32x4 (&v)[2][2][4][2], float (&tot)[2][4][2], LAS float* X, int wr, int wc, int fr, int fq) {
;     ...
;                 const f32x4 a = v[ai][bj][m][0], b = v[ai][bj][m][1];
;                 float s = (a[0] * a[0] + a[1] * a[1]) + (a[2] * a[2] + a[3] * a[3]) + (b[0] * b[0] + b[1] * b[1]) + (b[2] * b[2] + b[3] * b[3]);
;                 s += __shfl_xor(s, 16); s += __shfl_xor(s, 32);
;                 if (fq == 0) X[((ai * 128 + wr * 64 + m * 16 + fr) * 2 + bj) * 4 + wc] = s;
.LBB0_1059:
	s_or_b64 exec, exec, s[42:43]
	v_mul_f32_e32 v85, v85, v85
	v_fmac_f32_e32 v85, v84, v84
	v_mul_f32_e32 v84, v87, v87
	v_fmac_f32_e32 v84, v86, v86
	v_add_f32_e32 v84, v85, v84
	v_mul_f32_e32 v85, v99, v99
	v_fmac_f32_e32 v85, v98, v98
	v_mul_f32_e32 v79, v79, v79
	v_add_f32_e32 v84, v85, v84
	v_fmac_f32_e32 v79, v78, v78
	v_add_f32_e32 v78, v79, v84
	v_mov_b32_e32 v79, v78
	s_nop 1
	v_permlane16_swap_b32_e32 v79, v78
	s_waitcnt lgkmcnt(0)
	v_add_f32_e32 v78, v78, v79
	v_mov_b32_e32 v79, v78
	s_nop 1
	v_permlane32_swap_b32_e32 v79, v78
	s_and_saveexec_b64 s[42:43], s[0:1]
	s_cbranch_execz .LBB0_1061
	s_waitcnt lgkmcnt(0)
	v_add_f32_e32 v78, v78, v79
	ds_write_b32 v19, v78 offset:1040
.LBB0_1061:
	s_or_b64 exec, exec, s[42:43]
	v_mul_f32_e32 v78, v81, v81
	v_mul_f32_e32 v77, v77, v77
	v_fmac_f32_e32 v78, v80, v80
	v_fmac_f32_e32 v77, v76, v76
	v_mul_f32_e32 v73, v73, v73
	v_add_f32_e32 v76, v78, v77
	v_fmac_f32_e32 v73, v72, v72
	v_add_f32_e32 v72, v73, v76
	v_mul_f32_e32 v73, v75, v75
	v_fmac_f32_e32 v73, v74, v74
	v_add_f32_e32 v72, v73, v72
	v_mov_b32_e32 v73, v72
	s_nop 1
	v_permlane16_swap_b32_e32 v73, v72
	s_waitcnt lgkmcnt(0)
	v_add_f32_e32 v72, v72, v73
	v_mov_b32_e32 v73, v72
	s_nop 1
	v_permlane32_swap_b32_e32 v73, v72
	s_and_saveexec_b64 s[42:43], s[0:1]
	s_cbranch_execz .LBB0_1063
	s_waitcnt lgkmcnt(0)
	v_add_f32_e32 v72, v72, v73
	ds_write_b32 v19, v72 offset:1536
.LBB0_1063:
	s_or_b64 exec, exec, s[42:43]
	v_mul_f32_e32 v69, v69, v69
	v_fmac_f32_e32 v69, v68, v68
	v_mul_f32_e32 v68, v71, v71
	v_fmac_f32_e32 v68, v70, v70
	v_mul_f32_e32 v65, v65, v65
	v_add_f32_e32 v68, v69, v68
	v_fmac_f32_e32 v65, v64, v64
	v_add_f32_e32 v64, v65, v68
	v_mul_f32_e32 v65, v67, v67
	v_fmac_f32_e32 v65, v66, v66
	v_add_f32_e32 v64, v65, v64
	v_mov_b32_e32 v65, v64
	s_nop 1
	v_permlane16_swap_b32_e32 v65, v64
	s_waitcnt lgkmcnt(0)
	v_add_f32_e32 v64, v64, v65
	v_mov_b32_e32 v65, v64
	s_nop 1
	v_permlane32_swap_b32_e32 v65, v64
	s_and_saveexec_b64 s[42:43], s[0:1]
	s_cbranch_execz .LBB0_1065
	s_waitcnt lgkmcnt(0)
	v_add_f32_e32 v64, v64, v65
	ds_write_b32 v19, v64 offset:1552
.LBB0_1065:
	s_or_b64 exec, exec, s[42:43]
	v_mul_f32_e32 v61, v61, v61
	v_fmac_f32_e32 v61, v60, v60
	v_mul_f32_e32 v60, v63, v63
	v_fmac_f32_e32 v60, v62, v62
	v_mul_f32_e32 v57, v57, v57
	v_add_f32_e32 v60, v61, v60
	v_fmac_f32_e32 v57, v56, v56
	v_add_f32_e32 v56, v57, v60
	v_mul_f32_e32 v57, v59, v59
	v_fmac_f32_e32 v57, v58, v58
	v_add_f32_e32 v56, v57, v56
	v_mov_b32_e32 v57, v56
	s_nop 1
	v_permlane16_swap_b32_e32 v57, v56
	s_waitcnt lgkmcnt(0)
	v_add_f32_e32 v56, v56, v57
	v_mov_b32_e32 v57, v56
	s_nop 1
	v_permlane32_swap_b32_e32 v57, v56
	s_and_saveexec_b64 s[42:43], s[0:1]
	s_cbranch_execz .LBB0_1067
	s_waitcnt lgkmcnt(0)
	v_add_f32_e32 v56, v56, v57
	ds_write_b32 v19, v56 offset:4096
.LBB0_1067:
	s_or_b64 exec, exec, s[42:43]
	v_mul_f32_e32 v53, v53, v53
	v_fmac_f32_e32 v53, v52, v52
	v_mul_f32_e32 v52, v55, v55
	v_fmac_f32_e32 v52, v54, v54
	v_add_f32_e32 v52, v53, v52
	v_mul_f32_e32 v53, v83, v83
	v_fmac_f32_e32 v53, v82, v82
	v_mul_f32_e32 v47, v47, v47
	v_add_f32_e32 v52, v53, v52
	v_fmac_f32_e32 v47, v46, v46
	v_add_f32_e32 v46, v47, v52
	v_mov_b32_e32 v47, v46
	s_nop 1
	v_permlane16_swap_b32_e32 v47, v46
	s_waitcnt lgkmcnt(0)
	v_add_f32_e32 v46, v46, v47
	v_mov_b32_e32 v47, v46
	s_nop 1
	v_permlane32_swap_b32_e32 v47, v46
	s_and_saveexec_b64 s[42:43], s[0:1]
	s_cbranch_execz .LBB0_1069
	s_waitcnt lgkmcnt(0)
	v_add_f32_e32 v46, v46, v47
	ds_write_b32 v19, v46 offset:4112
; __device__ __forceinline__ void head_ss(const f32x4 (&v)[2][2][4][2], float (&tot)[2][4][2], LAS float* X, int wr, int wc, int fr, int fq) {
;     ...
;                 const f32x4 a = v[ai][bj][m][0], b = v[ai][bj][m][1];
;                 float s = (a[0] * a[0] + a[1] * a[1]) + (a[2] * a[2] + a[3] * a[3]) + (b[0] * b[0] + b[1] * b[1]) + (b[2] * b[2] + b[3] * b[3]);
;                 s += __shfl_xor(s, 16); s += __shfl_xor(s, 32);
;                 if (fq == 0) X[((ai * 128 + wr * 64 + m * 16 + fr) * 2 + bj) * 4 + wc] = s;
.LBB0_1069:
	s_or_b64 exec, exec, s[42:43]
	v_mul_f32_e32 v46, v49, v49
	v_mul_f32_e32 v45, v45, v45
	v_fmac_f32_e32 v46, v48, v48
	v_fmac_f32_e32 v45, v44, v44
	v_mul_f32_e32 v41, v41, v41
	v_add_f32_e32 v44, v46, v45
	v_fmac_f32_e32 v41, v40, v40
	v_add_f32_e32 v40, v41, v44
	v_mul_f32_e32 v41, v43, v43
	v_fmac_f32_e32 v41, v42, v42
	v_add_f32_e32 v40, v41, v40
	v_mov_b32_e32 v41, v40
	s_nop 1
	v_permlane16_swap_b32_e32 v41, v40
	s_waitcnt lgkmcnt(0)
	v_add_f32_e32 v40, v40, v41
	v_mov_b32_e32 v41, v40
	s_nop 1
	v_permlane32_swap_b32_e32 v41, v40
	s_and_saveexec_b64 s[42:43], s[0:1]
	s_cbranch_execz .LBB0_1071
	s_waitcnt lgkmcnt(0)
	v_add_f32_e32 v40, v40, v41
	ds_write_b32 v19, v40 offset:4608
.LBB0_1071:
	s_or_b64 exec, exec, s[42:43]
	v_mul_f32_e32 v37, v37, v37
	v_fmac_f32_e32 v37, v36, v36
	v_mul_f32_e32 v36, v39, v39
	v_fmac_f32_e32 v36, v38, v38
	v_add_f32_e32 v36, v37, v36
	v_mul_f32_e32 v37, v51, v51
	v_fmac_f32_e32 v37, v50, v50
	v_mul_f32_e32 v31, v31, v31
	v_add_f32_e32 v36, v37, v36
	v_fmac_f32_e32 v31, v30, v30
	v_add_f32_e32 v30, v31, v36
	v_mov_b32_e32 v31, v30
	s_nop 1
	v_permlane16_swap_b32_e32 v31, v30
	s_waitcnt lgkmcnt(0)
	v_add_f32_e32 v30, v30, v31
	v_mov_b32_e32 v31, v30
	s_nop 1
	v_permlane32_swap_b32_e32 v31, v30
	s_and_saveexec_b64 s[42:43], s[0:1]
	s_cbranch_execz .LBB0_1073
	s_waitcnt lgkmcnt(0)
	v_add_f32_e32 v30, v30, v31
	ds_write_b32 v19, v30 offset:4624
.LBB0_1073:
	s_or_b64 exec, exec, s[42:43]
	v_mul_f32_e32 v30, v33, v33
	v_mul_f32_e32 v29, v29, v29
	v_fmac_f32_e32 v30, v32, v32
	v_fmac_f32_e32 v29, v28, v28
	v_mul_f32_e32 v25, v25, v25
	v_add_f32_e32 v28, v30, v29
	v_fmac_f32_e32 v25, v24, v24
	v_add_f32_e32 v24, v25, v28
	v_mul_f32_e32 v25, v27, v27
	v_fmac_f32_e32 v25, v26, v26
	v_add_f32_e32 v24, v25, v24
	v_mov_b32_e32 v25, v24
	s_nop 1
	v_permlane16_swap_b32_e32 v25, v24
	s_waitcnt lgkmcnt(0)
	v_add_f32_e32 v24, v24, v25
	v_mov_b32_e32 v25, v24
	s_nop 1
	v_permlane32_swap_b32_e32 v25, v24
	s_and_saveexec_b64 s[42:43], s[0:1]
	s_cbranch_execz .LBB0_1075
	s_waitcnt lgkmcnt(0)
	v_add_f32_e32 v24, v24, v25
	ds_write_b32 v19, v24 offset:5120
.LBB0_1075:
	s_or_b64 exec, exec, s[42:43]
	v_mul_f32_e32 v21, v21, v21
	v_fmac_f32_e32 v21, v20, v20
	v_mul_f32_e32 v20, v23, v23
	v_fmac_f32_e32 v20, v22, v22
	v_add_f32_e32 v20, v21, v20
	v_mul_f32_e32 v21, v35, v35
	v_fmac_f32_e32 v21, v34, v34
	v_mul_f32_e32 v15, v15, v15
	v_add_f32_e32 v20, v21, v20
	v_fmac_f32_e32 v15, v14, v14
	v_add_f32_e32 v14, v15, v20
	v_mov_b32_e32 v15, v14
	s_nop 1
	v_permlane16_swap_b32_e32 v15, v14
	s_waitcnt lgkmcnt(0)
	v_add_f32_e32 v14, v14, v15
	v_mov_b32_e32 v15, v14
	s_nop 1
	v_permlane32_swap_b32_e32 v15, v14
	s_and_saveexec_b64 s[42:43], s[0:1]
	s_cbranch_execz .LBB0_1077
	s_waitcnt lgkmcnt(0)
	v_add_f32_e32 v14, v14, v15
	ds_write_b32 v19, v14 offset:5136
.LBB0_1077:
	s_or_b64 exec, exec, s[42:43]
	v_mul_f32_e32 v14, v17, v17
	v_mul_f32_e32 v13, v13, v13
	v_fmac_f32_e32 v14, v16, v16
	v_fmac_f32_e32 v13, v12, v12
	v_mul_f32_e32 v9, v9, v9
	v_add_f32_e32 v12, v14, v13
	v_fmac_f32_e32 v9, v8, v8
	v_add_f32_e32 v8, v9, v12
	v_mul_f32_e32 v9, v11, v11
	v_fmac_f32_e32 v9, v10, v10
	v_add_f32_e32 v8, v9, v8
	v_mov_b32_e32 v9, v8
	s_nop 1
	v_permlane16_swap_b32_e32 v9, v8
	s_waitcnt lgkmcnt(0)
	v_add_f32_e32 v8, v8, v9
	v_mov_b32_e32 v9, v8
	s_nop 1
	v_permlane32_swap_b32_e32 v9, v8
	s_and_saveexec_b64 s[42:43], s[0:1]
	s_cbranch_execz .LBB0_1079
	s_waitcnt lgkmcnt(0)
	v_add_f32_e32 v8, v8, v9
	ds_write_b32 v19, v8 offset:5632
.LBB0_1079:
	s_or_b64 exec, exec, s[42:43]
	v_mul_f32_e32 v5, v5, v5
	v_fmac_f32_e32 v5, v4, v4
	v_mul_f32_e32 v4, v7, v7
	v_fmac_f32_e32 v4, v6, v6
	v_mul_f32_e32 v1, v1, v1
	v_add_f32_e32 v4, v5, v4
	v_fmac_f32_e32 v1, v0, v0
	v_add_f32_e32 v0, v1, v4
	v_mul_f32_e32 v1, v3, v3
	v_fmac_f32_e32 v1, v2, v2
	v_add_f32_e32 v0, v1, v0
	v_mov_b32_e32 v1, v0
	s_nop 1
	v_permlane16_swap_b32_e32 v1, v0
	s_waitcnt lgkmcnt(0)
	v_add_f32_e32 v0, v0, v1
	v_mov_b32_e32 v1, v0
	s_nop 1
	v_permlane32_swap_b32_e32 v1, v0
	s_and_saveexec_b64 s[42:43], s[0:1]
	s_cbranch_execz .LBB0_1081
	s_waitcnt lgkmcnt(0)
	v_add_f32_e32 v0, v0, v1
	ds_write_b32 v19, v0 offset:5648
